# u2 plus: first K-iteration of every GEMM tile peeled, accumulators start from MFMA C=0 instead of 128 v_mov zero-inits per tile
# baseline (speedup 1.0000x reference)
; #define PG8_STAGE(bufoff, gbase, voff) do { _Pragma("unroll") for (int _i = 0; _i < 2; ++_i) \
;         __builtin_amdgcn_global_load_lds((const unsigned*)((const char*)(gbase) + (voff)[_i]), (PG8_LAS unsigned*)(lds + (bufoff) + ldsw + _i * 8192), 16, 0, 0); } while (0)
; #define PG8_LDA(dst, b, h) do { _Pragma("unroll") for (int m = 0; m < 4; ++m) _Pragma("unroll") for (int k = 0; k < 2; ++k) dst[m][k] = *(const PG8_LAS bf16x8*)(lds + PG8_SA(b, h) + aoff + m * 2048 + k * 1024); } while (0)
; #define PG8_LDB(dst, b, h) do { _Pragma("unroll") for (int n = 0; n < 2; ++n) _Pragma("unroll") for (int k = 0; k < 2; ++k) dst[n][k] = *(const PG8_LAS bf16x8*)(lds + PG8_SB(b, h) + boff + n * 2048 + k * 1024); } while (0)
; #define PG8_WAIT_V(n) asm volatile("s_waitcnt vmcnt(" #n ")" ::: "memory")
; #define PG8_WAIT_L(n) asm volatile("s_waitcnt lgkmcnt(" #n ")" ::: "memory")
; #define PG8_BAR __builtin_amdgcn_s_barrier()
; #define PG8_SCHED __builtin_amdgcn_sched_barrier(0)
; template <class Epi, class Sched, bool ALIGN_EPI = false, bool SP2 = false>
; __device__ __forceinline__ void gemm_phase(PG8_LAS unsigned char* lds, const Gemm g, const Sched& S, const Epi& E, int tid_in) {
;     ...
;     for (;;) {
;         const bool has_next = S.next(ui + 1, nxt);
;         const char* nA = has_next ? (const char*)g.A + (size_t)nxt.pm * tstep : cA; const char* nB = has_next ? (const char*)g.Bt + (size_t)nxt.pn * tstep : cB;
;         for (int t = 0; t < nt; t += 2) {
;             const bool last = (t == nt - 2);
;             const char* a1 = cA + (size_t)(t + 1) * kstep;
;             const char* a2 = last ? nA : cA + (size_t)(t + 2) * kstep; const char* b2 = last ? nB : cB + (size_t)(t + 2) * kstep;
;             const char* a3 = a2 + kstep; const char* b3 = b2 + kstep;
;             if (last && has_next) S.a_ready(nxt);
;             if constexpr (SP2) {
;             PG8_LDB(B0, 0, 0); PG8_LDB(B1, 0, 1); PG8_SCHED; PG8_LDA(At, 0, 0); PG8_STAGE(PG8_SA(1, 1), a1 + hstep, voffA);
;             PG8_WAIT_V(8); PG8_WAIT_L(0); PG8_BAR; PG8_MMA(0, 0, At, B0); PG8_MMA(0, 1, At, B1); PG8_BAR; PG8_SCHED;
;             PG8_LDA(At, 0, 1); PG8_STAGE(PG8_SB(0, 0), b2, voffB); PG8_STAGE(PG8_SB(0, 1), b2 + hstep, voffB); PG8_STAGE(PG8_SA(0, 0), a2, voffA);
;             PG8_WAIT_V(8); PG8_WAIT_L(0); PG8_BAR; PG8_MMA(1, 0, At, B0); PG8_MMA(1, 1, At, B1); PG8_BAR; PG8_SCHED;
.LBB0_124:
	s_ashr_i32 s63, s62, 31
	s_lshl_b64 s[6:7], s[62:63], 20
	s_add_u32 s64, s12, s6
	s_addc_u32 s65, s14, s7
	s_and_b64 s[6:7], s[4:5], exec
	s_cselect_b32 s63, s65, s75
	s_cselect_b32 s71, s64, s74
	s_ashr_i32 s61, s60, 31
	s_lshl_b64 s[6:7], s[60:61], 20
	s_add_u32 s66, s50, s6
	s_addc_u32 s67, s51, s7
	s_and_b64 s[6:7], s[4:5], exec
	s_cselect_b32 s61, s67, s73
	s_cselect_b32 s85, s66, s72
	s_add_u32 s6, s74, 0x80080
	s_addc_u32 s7, s75, 0
	s_add_u32 s87, s72, 0x100
	s_addc_u32 s90, s73, 0
	s_mov_b32 s95, -2
	s_waitcnt vmcnt(0)
	s_add_u32 s24, s6, 0xfff80080
	s_addc_u32 s25, s7, -1
	s_add_i32 s96, 0, 0x10000
	s_cmp_eq_u32 s95, 28
	s_cselect_b32 s75, s63, s25
	s_cselect_b32 s74, s71, s24
	s_cselect_b32 s73, s61, s90
	s_cselect_b32 s72, s85, s87
	s_add_i32 s24, 0, 0x14000
	v_add_u32_e32 v154, s96, v165
	v_add_u32_e32 v162, s24, v165
	ds_read_b128 v[142:145], v154
	ds_read_b128 v[146:149], v154 offset:1024
	ds_read_b128 v[150:153], v154 offset:2048
	ds_read_b128 v[154:157], v154 offset:3072
	ds_read_b128 v[158:161], v162
	ds_read_b128 v[170:173], v162 offset:1024
	ds_read_b128 v[174:177], v162 offset:2048
	ds_read_b128 v[178:181], v162 offset:3072
	v_lshl_add_u64 v[162:163], s[6:7], 0, v[138:139]
	s_add_i32 m0, s16, 0xc000
	ds_read_b128 v[182:185], v169
	ds_read_b128 v[186:189], v169 offset:1024
	ds_read_b128 v[190:193], v169 offset:2048
	ds_read_b128 v[194:197], v169 offset:3072
	ds_read_b128 v[198:201], v169 offset:4096
	ds_read_b128 v[202:205], v169 offset:5120
	ds_read_b128 v[206:209], v169 offset:6144
	ds_read_b128 v[210:213], v169 offset:7168
	global_load_lds_dwordx4 v[162:163], off
	v_lshl_add_u64 v[162:163], s[6:7], 0, v[140:141]
	s_add_i32 m0, s16, 0xe000
	s_nop 0
	global_load_lds_dwordx4 v[162:163], off
	s_waitcnt vmcnt(8)
	s_waitcnt lgkmcnt(0)
	s_setprio 1
	s_barrier
	v_mfma_f32_16x16x32_bf16 v[126:129], v[142:145], v[182:185], 0
	v_mfma_f32_16x16x32_bf16 v[122:125], v[150:153], v[182:185], 0
	v_mfma_f32_16x16x32_bf16 v[110:113], v[142:145], v[190:193], 0
	v_mfma_f32_16x16x32_bf16 v[106:109], v[150:153], v[190:193], 0
	v_mfma_f32_16x16x32_bf16 v[94:97], v[142:145], v[198:201], 0
	v_mfma_f32_16x16x32_bf16 v[90:93], v[150:153], v[198:201], 0
	v_mfma_f32_16x16x32_bf16 v[78:81], v[142:145], v[206:209], 0
	v_mfma_f32_16x16x32_bf16 v[74:77], v[150:153], v[206:209], 0
	v_mfma_f32_16x16x32_bf16 v[126:129], v[146:149], v[186:189], v[126:129]
	v_mfma_f32_16x16x32_bf16 v[122:125], v[154:157], v[186:189], v[122:125]
	v_mfma_f32_16x16x32_bf16 v[110:113], v[146:149], v[194:197], v[110:113]
	v_mfma_f32_16x16x32_bf16 v[106:109], v[154:157], v[194:197], v[106:109]
	v_mfma_f32_16x16x32_bf16 v[94:97], v[146:149], v[202:205], v[94:97]
	v_mfma_f32_16x16x32_bf16 v[90:93], v[154:157], v[202:205], v[90:93]
	v_mfma_f32_16x16x32_bf16 v[78:81], v[146:149], v[210:213], v[78:81]
	v_mfma_f32_16x16x32_bf16 v[74:77], v[154:157], v[210:213], v[74:77]
	v_mfma_f32_16x16x32_bf16 v[118:121], v[158:161], v[182:185], 0
	v_mfma_f32_16x16x32_bf16 v[114:117], v[174:177], v[182:185], 0
	v_mfma_f32_16x16x32_bf16 v[102:105], v[158:161], v[190:193], 0
	v_mfma_f32_16x16x32_bf16 v[98:101], v[174:177], v[190:193], 0
	v_mfma_f32_16x16x32_bf16 v[86:89], v[158:161], v[198:201], 0
	v_mfma_f32_16x16x32_bf16 v[82:85], v[174:177], v[198:201], 0
	v_mfma_f32_16x16x32_bf16 v[70:73], v[158:161], v[206:209], 0
	v_mfma_f32_16x16x32_bf16 v[66:69], v[174:177], v[206:209], 0
	v_mfma_f32_16x16x32_bf16 v[118:121], v[170:173], v[186:189], v[118:121]
	v_mfma_f32_16x16x32_bf16 v[114:117], v[178:181], v[186:189], v[114:117]
	v_mfma_f32_16x16x32_bf16 v[102:105], v[170:173], v[194:197], v[102:105]
	v_mfma_f32_16x16x32_bf16 v[98:101], v[178:181], v[194:197], v[98:101]
	v_mfma_f32_16x16x32_bf16 v[86:89], v[170:173], v[202:205], v[86:89]
	v_mfma_f32_16x16x32_bf16 v[82:85], v[178:181], v[202:205], v[82:85]
	v_mfma_f32_16x16x32_bf16 v[70:73], v[170:173], v[210:213], v[70:73]
	v_mfma_f32_16x16x32_bf16 v[66:69], v[178:181], v[210:213], v[66:69]
	s_barrier
	s_setprio 0
	s_add_i32 s25, s96, s15
	v_lshl_add_u64 v[162:163], s[72:73], 0, v[132:133]
	s_mov_b32 m0, s25
	ds_read_b128 v[182:185], v169 offset:16384
	ds_read_b128 v[186:189], v169 offset:17408
	ds_read_b128 v[190:193], v169 offset:18432
	ds_read_b128 v[194:197], v169 offset:19456
	ds_read_b128 v[198:201], v169 offset:20480
	ds_read_b128 v[202:205], v169 offset:21504
	ds_read_b128 v[206:209], v169 offset:22528
	ds_read_b128 v[210:213], v169 offset:23552
	global_load_lds_dwordx4 v[162:163], off
	s_add_i32 m0, s25, 0x2000
	s_add_u32 s96, s72, 0x80000
	v_lshl_add_u64 v[166:167], s[72:73], 0, v[136:137]
	s_addc_u32 s97, s73, 0
	s_add_i32 s24, s24, s15
	global_load_lds_dwordx4 v[166:167], off
	v_lshl_add_u64 v[218:219], s[96:97], 0, v[132:133]
	s_mov_b32 m0, s24
	v_lshl_add_u64 v[220:221], s[74:75], 0, v[134:135]
	global_load_lds_dwordx4 v[218:219], off
	v_lshl_add_u64 v[218:219], s[96:97], 0, v[136:137]
	s_add_i32 m0, s24, 0x2000
	s_nop 0
	global_load_lds_dwordx4 v[218:219], off
	v_lshl_add_u64 v[218:219], s[74:75], 0, v[130:131]
	s_mov_b32 m0, s16
	s_nop 0
	global_load_lds_dwordx4 v[218:219], off
	s_mov_b32 m0, s26
	s_nop 0
	global_load_lds_dwordx4 v[220:221], off
	s_waitcnt vmcnt(8)
	s_waitcnt lgkmcnt(0)
	s_setprio 1
	s_barrier
; #define PG8_STAGE(bufoff, gbase, voff) do { _Pragma("unroll") for (int _i = 0; _i < 2; ++_i) \
;         __builtin_amdgcn_global_load_lds((const unsigned*)((const char*)(gbase) + (voff)[_i]), (PG8_LAS unsigned*)(lds + (bufoff) + ldsw + _i * 8192), 16, 0, 0); } while (0)
; #define PG8_LDA(dst, b, h) do { _Pragma("unroll") for (int m = 0; m < 4; ++m) _Pragma("unroll") for (int k = 0; k < 2; ++k) dst[m][k] = *(const PG8_LAS bf16x8*)(lds + PG8_SA(b, h) + aoff + m * 2048 + k * 1024); } while (0)
; #define PG8_LDB(dst, b, h) do { _Pragma("unroll") for (int n = 0; n < 2; ++n) _Pragma("unroll") for (int k = 0; k < 2; ++k) dst[n][k] = *(const PG8_LAS bf16x8*)(lds + PG8_SB(b, h) + boff + n * 2048 + k * 1024); } while (0)
; #define PG8_MMA(ai, bj, At, Bt) do { __builtin_amdgcn_s_setprio(1); _Pragma("unroll") for (int m = 0; m < 4; ++m) _Pragma("unroll") for (int n = 0; n < 2; ++n) _Pragma("unroll") for (int k = 0; k < 2; ++k) \
;         acc[ai][bj][m][n] = __builtin_amdgcn_mfma_f32_16x16x32_bf16(Bt[n][k], At[m][k], acc[ai][bj][m][n], 0, 0, 0); __builtin_amdgcn_s_setprio(0); } while (0)
; #define PG8_WAIT_V(n) asm volatile("s_waitcnt vmcnt(" #n ")" ::: "memory")
; #define PG8_WAIT_L(n) asm volatile("s_waitcnt lgkmcnt(" #n ")" ::: "memory")
; #define PG8_BAR __builtin_amdgcn_s_barrier()
; #define PG8_SCHED __builtin_amdgcn_sched_barrier(0)
; template <class Epi, class Sched, bool ALIGN_EPI = false, bool SP2 = false>
; __device__ __forceinline__ void gemm_phase(PG8_LAS unsigned char* lds, const Gemm g, const Sched& S, const Epi& E, int tid_in) {
;     ...
;             PG8_WAIT_V(8); PG8_WAIT_L(0); PG8_BAR; PG8_MMA(1, 0, At, B0); PG8_MMA(1, 1, At, B1); PG8_BAR; PG8_SCHED;
;             PG8_LDB(B0, 1, 0); PG8_LDB(B1, 1, 1); PG8_SCHED; PG8_LDA(At, 1, 0); PG8_STAGE(PG8_SA(0, 1), a2 + hstep, voffA);
;             PG8_WAIT_V(8); PG8_WAIT_L(0); PG8_BAR; PG8_MMA(0, 0, At, B0); PG8_MMA(0, 1, At, B1); PG8_BAR; PG8_SCHED;
	v_mfma_f32_16x16x32_bf16 v[62:65], v[142:145], v[182:185], 0
	v_mfma_f32_16x16x32_bf16 v[58:61], v[150:153], v[182:185], 0
	v_mfma_f32_16x16x32_bf16 v[46:49], v[142:145], v[190:193], 0
	v_mfma_f32_16x16x32_bf16 v[42:45], v[150:153], v[190:193], 0
	v_mfma_f32_16x16x32_bf16 v[30:33], v[142:145], v[198:201], 0
	v_mfma_f32_16x16x32_bf16 v[26:29], v[150:153], v[198:201], 0
	v_mfma_f32_16x16x32_bf16 v[12:15], v[142:145], v[206:209], 0
	v_mfma_f32_16x16x32_bf16 v[8:11], v[150:153], v[206:209], 0
	v_mfma_f32_16x16x32_bf16 v[62:65], v[146:149], v[186:189], v[62:65]
	v_mfma_f32_16x16x32_bf16 v[58:61], v[154:157], v[186:189], v[58:61]
	v_mfma_f32_16x16x32_bf16 v[46:49], v[146:149], v[194:197], v[46:49]
	v_mfma_f32_16x16x32_bf16 v[42:45], v[154:157], v[194:197], v[42:45]
	v_mfma_f32_16x16x32_bf16 v[30:33], v[146:149], v[202:205], v[30:33]
	v_mfma_f32_16x16x32_bf16 v[26:29], v[154:157], v[202:205], v[26:29]
	v_mfma_f32_16x16x32_bf16 v[12:15], v[146:149], v[210:213], v[12:15]
	v_mfma_f32_16x16x32_bf16 v[8:11], v[154:157], v[210:213], v[8:11]
	v_mfma_f32_16x16x32_bf16 v[54:57], v[158:161], v[182:185], 0
	v_mfma_f32_16x16x32_bf16 v[50:53], v[174:177], v[182:185], 0
	v_mfma_f32_16x16x32_bf16 v[38:41], v[158:161], v[190:193], 0
	v_mfma_f32_16x16x32_bf16 v[34:37], v[174:177], v[190:193], 0
	v_mfma_f32_16x16x32_bf16 v[22:25], v[158:161], v[198:201], 0
	v_mfma_f32_16x16x32_bf16 v[16:19], v[174:177], v[198:201], 0
	v_mfma_f32_16x16x32_bf16 v[4:7], v[158:161], v[206:209], 0
	v_mfma_f32_16x16x32_bf16 v[0:3], v[174:177], v[206:209], 0
	v_mfma_f32_16x16x32_bf16 v[54:57], v[170:173], v[186:189], v[54:57]
	v_mfma_f32_16x16x32_bf16 v[50:53], v[178:181], v[186:189], v[50:53]
	v_mfma_f32_16x16x32_bf16 v[38:41], v[170:173], v[194:197], v[38:41]
	v_mfma_f32_16x16x32_bf16 v[34:37], v[178:181], v[194:197], v[34:37]
	v_mfma_f32_16x16x32_bf16 v[22:25], v[170:173], v[202:205], v[22:25]
	v_mfma_f32_16x16x32_bf16 v[16:19], v[178:181], v[202:205], v[16:19]
	v_mfma_f32_16x16x32_bf16 v[4:7], v[170:173], v[210:213], v[4:7]
	v_mfma_f32_16x16x32_bf16 v[0:3], v[178:181], v[210:213], v[0:3]
	s_barrier
	s_setprio 0
	s_add_i32 s24, 0, 0x18000
	s_add_i32 s25, 0, 0x1c000
	v_add_u32_e32 v154, s24, v165
	v_add_u32_e32 v164, s25, v165
	ds_read_b128 v[142:145], v154
	ds_read_b128 v[146:149], v154 offset:1024
	ds_read_b128 v[150:153], v154 offset:2048
	ds_read_b128 v[154:157], v154 offset:3072
	ds_read_b128 v[158:161], v164
	ds_read_b128 v[170:173], v164 offset:1024
	ds_read_b128 v[174:177], v164 offset:2048
	ds_read_b128 v[178:181], v164 offset:3072
	s_add_u32 s74, s74, 0x80000
	s_addc_u32 s75, s75, 0
	s_mov_b32 m0, s27
	v_lshl_add_u64 v[222:223], s[74:75], 0, v[130:131]
	ds_read_b128 v[182:185], v169 offset:32768
	ds_read_b128 v[186:189], v169 offset:33792
	ds_read_b128 v[190:193], v169 offset:34816
	ds_read_b128 v[194:197], v169 offset:35840
	ds_read_b128 v[198:201], v169 offset:36864
	ds_read_b128 v[202:205], v169 offset:37888
	ds_read_b128 v[206:209], v169 offset:38912
	ds_read_b128 v[210:213], v169 offset:39936
	global_load_lds_dwordx4 v[222:223], off
	v_lshl_add_u64 v[222:223], s[74:75], 0, v[134:135]
	s_mov_b32 m0, s34
	s_nop 0
	global_load_lds_dwordx4 v[222:223], off
	s_waitcnt vmcnt(8)
	s_waitcnt lgkmcnt(0)
	s_setprio 1
	s_barrier
	v_mfma_f32_16x16x32_bf16 v[126:129], v[142:145], v[182:185], v[126:129]
	v_mfma_f32_16x16x32_bf16 v[122:125], v[150:153], v[182:185], v[122:125]
	v_mfma_f32_16x16x32_bf16 v[110:113], v[142:145], v[190:193], v[110:113]
	v_mfma_f32_16x16x32_bf16 v[106:109], v[150:153], v[190:193], v[106:109]
	v_mfma_f32_16x16x32_bf16 v[94:97], v[142:145], v[198:201], v[94:97]
	v_mfma_f32_16x16x32_bf16 v[90:93], v[150:153], v[198:201], v[90:93]
	v_mfma_f32_16x16x32_bf16 v[78:81], v[142:145], v[206:209], v[78:81]
	v_mfma_f32_16x16x32_bf16 v[74:77], v[150:153], v[206:209], v[74:77]
	v_mfma_f32_16x16x32_bf16 v[126:129], v[146:149], v[186:189], v[126:129]
	v_mfma_f32_16x16x32_bf16 v[122:125], v[154:157], v[186:189], v[122:125]
	v_mfma_f32_16x16x32_bf16 v[110:113], v[146:149], v[194:197], v[110:113]
	v_mfma_f32_16x16x32_bf16 v[106:109], v[154:157], v[194:197], v[106:109]
	v_mfma_f32_16x16x32_bf16 v[94:97], v[146:149], v[202:205], v[94:97]
	v_mfma_f32_16x16x32_bf16 v[90:93], v[154:157], v[202:205], v[90:93]
	v_mfma_f32_16x16x32_bf16 v[78:81], v[146:149], v[210:213], v[78:81]
	v_mfma_f32_16x16x32_bf16 v[74:77], v[154:157], v[210:213], v[74:77]
	v_mfma_f32_16x16x32_bf16 v[118:121], v[158:161], v[182:185], v[118:121]
	v_mfma_f32_16x16x32_bf16 v[114:117], v[174:177], v[182:185], v[114:117]
	v_mfma_f32_16x16x32_bf16 v[102:105], v[158:161], v[190:193], v[102:105]
	v_mfma_f32_16x16x32_bf16 v[98:101], v[174:177], v[190:193], v[98:101]
	v_mfma_f32_16x16x32_bf16 v[86:89], v[158:161], v[198:201], v[86:89]
	v_mfma_f32_16x16x32_bf16 v[82:85], v[174:177], v[198:201], v[82:85]
	v_mfma_f32_16x16x32_bf16 v[70:73], v[158:161], v[206:209], v[70:73]
	v_mfma_f32_16x16x32_bf16 v[66:69], v[174:177], v[206:209], v[66:69]
	v_mfma_f32_16x16x32_bf16 v[118:121], v[170:173], v[186:189], v[118:121]
	v_mfma_f32_16x16x32_bf16 v[114:117], v[178:181], v[186:189], v[114:117]
	v_mfma_f32_16x16x32_bf16 v[102:105], v[170:173], v[194:197], v[102:105]
	v_mfma_f32_16x16x32_bf16 v[98:101], v[178:181], v[194:197], v[98:101]
	v_mfma_f32_16x16x32_bf16 v[86:89], v[170:173], v[202:205], v[86:89]
	v_mfma_f32_16x16x32_bf16 v[82:85], v[178:181], v[202:205], v[82:85]
	v_mfma_f32_16x16x32_bf16 v[70:73], v[170:173], v[210:213], v[70:73]
	v_mfma_f32_16x16x32_bf16 v[66:69], v[178:181], v[210:213], v[66:69]
	s_barrier
; #define PG8_STAGE(bufoff, gbase, voff) do { _Pragma("unroll") for (int _i = 0; _i < 2; ++_i) \
;         __builtin_amdgcn_global_load_lds((const unsigned*)((const char*)(gbase) + (voff)[_i]), (PG8_LAS unsigned*)(lds + (bufoff) + ldsw + _i * 8192), 16, 0, 0); } while (0)
; #define PG8_LDA(dst, b, h) do { _Pragma("unroll") for (int m = 0; m < 4; ++m) _Pragma("unroll") for (int k = 0; k < 2; ++k) dst[m][k] = *(const PG8_LAS bf16x8*)(lds + PG8_SA(b, h) + aoff + m * 2048 + k * 1024); } while (0)
; #define PG8_MMA(ai, bj, At, Bt) do { __builtin_amdgcn_s_setprio(1); _Pragma("unroll") for (int m = 0; m < 4; ++m) _Pragma("unroll") for (int n = 0; n < 2; ++n) _Pragma("unroll") for (int k = 0; k < 2; ++k) \
;         acc[ai][bj][m][n] = __builtin_amdgcn_mfma_f32_16x16x32_bf16(Bt[n][k], At[m][k], acc[ai][bj][m][n], 0, 0, 0); __builtin_amdgcn_s_setprio(0); } while (0)
; #define PG8_WAIT_V(n) asm volatile("s_waitcnt vmcnt(" #n ")" ::: "memory")
; #define PG8_WAIT_L(n) asm volatile("s_waitcnt lgkmcnt(" #n ")" ::: "memory")
; #define PG8_BAR __builtin_amdgcn_s_barrier()
; #define PG8_SCHED __builtin_amdgcn_sched_barrier(0)
; template <class Epi, class Sched, bool ALIGN_EPI = false, bool SP2 = false>
; __device__ __forceinline__ void gemm_phase(PG8_LAS unsigned char* lds, const Gemm g, const Sched& S, const Epi& E, int tid_in) {
;     ...
;             PG8_LDA(At, 1, 1); PG8_STAGE(PG8_SB(1, 0), b3, voffB); PG8_STAGE(PG8_SB(1, 1), b3 + hstep, voffB); PG8_STAGE(PG8_SA(1, 0), a3, voffA);
;             PG8_WAIT_V(8); PG8_WAIT_L(0); PG8_BAR; PG8_MMA(1, 0, At, B0); PG8_MMA(1, 1, At, B1); PG8_BAR; PG8_SCHED;
	s_setprio 0
	s_add_i32 s24, s24, s15
	v_lshl_add_u64 v[162:163], v[162:163], 0, s[22:23]
	s_mov_b32 m0, s24
	ds_read_b128 v[182:185], v169 offset:49152
	ds_read_b128 v[186:189], v169 offset:50176
	ds_read_b128 v[190:193], v169 offset:51200
	ds_read_b128 v[194:197], v169 offset:52224
	ds_read_b128 v[198:201], v169 offset:53248
	ds_read_b128 v[202:205], v169 offset:54272
	ds_read_b128 v[206:209], v169 offset:55296
	ds_read_b128 v[210:213], v169 offset:56320
	global_load_lds_dwordx4 v[162:163], off
	s_add_i32 m0, s24, 0x2000
	s_add_u32 s72, s72, 0x80080
	v_lshl_add_u64 v[162:163], v[166:167], 0, s[22:23]
	s_addc_u32 s73, s73, 0
	s_add_i32 s24, s25, s15
	global_load_lds_dwordx4 v[162:163], off
	v_lshl_add_u64 v[162:163], s[72:73], 0, v[132:133]
	s_mov_b32 m0, s24
	s_nop 0
	global_load_lds_dwordx4 v[162:163], off
	v_lshl_add_u64 v[162:163], s[72:73], 0, v[136:137]
	s_add_i32 m0, s24, 0x2000
	s_nop 0
	global_load_lds_dwordx4 v[162:163], off
	v_lshl_add_u64 v[162:163], v[218:219], 0, s[22:23]
	s_mov_b32 m0, s69
	s_nop 0
	global_load_lds_dwordx4 v[162:163], off
	v_lshl_add_u64 v[162:163], v[220:221], 0, s[22:23]
	s_mov_b32 m0, s81
	s_nop 0
	global_load_lds_dwordx4 v[162:163], off
	s_waitcnt vmcnt(8)
	s_waitcnt lgkmcnt(0)
	s_setprio 1
	s_barrier
	v_mfma_f32_16x16x32_bf16 v[62:65], v[142:145], v[182:185], v[62:65]
	v_mfma_f32_16x16x32_bf16 v[58:61], v[150:153], v[182:185], v[58:61]
	v_mfma_f32_16x16x32_bf16 v[46:49], v[142:145], v[190:193], v[46:49]
	v_mfma_f32_16x16x32_bf16 v[42:45], v[150:153], v[190:193], v[42:45]
	v_mfma_f32_16x16x32_bf16 v[30:33], v[142:145], v[198:201], v[30:33]
	v_mfma_f32_16x16x32_bf16 v[26:29], v[150:153], v[198:201], v[26:29]
	v_mfma_f32_16x16x32_bf16 v[12:15], v[142:145], v[206:209], v[12:15]
	v_mfma_f32_16x16x32_bf16 v[8:11], v[150:153], v[206:209], v[8:11]
	v_mfma_f32_16x16x32_bf16 v[62:65], v[146:149], v[186:189], v[62:65]
	v_mfma_f32_16x16x32_bf16 v[58:61], v[154:157], v[186:189], v[58:61]
	v_mfma_f32_16x16x32_bf16 v[46:49], v[146:149], v[194:197], v[46:49]
	v_mfma_f32_16x16x32_bf16 v[42:45], v[154:157], v[194:197], v[42:45]
	v_mfma_f32_16x16x32_bf16 v[30:33], v[146:149], v[202:205], v[30:33]
	v_mfma_f32_16x16x32_bf16 v[26:29], v[154:157], v[202:205], v[26:29]
	v_mfma_f32_16x16x32_bf16 v[12:15], v[146:149], v[210:213], v[12:15]
	v_mfma_f32_16x16x32_bf16 v[8:11], v[154:157], v[210:213], v[8:11]
	v_mfma_f32_16x16x32_bf16 v[54:57], v[158:161], v[182:185], v[54:57]
	v_mfma_f32_16x16x32_bf16 v[50:53], v[174:177], v[182:185], v[50:53]
	v_mfma_f32_16x16x32_bf16 v[38:41], v[158:161], v[190:193], v[38:41]
	v_mfma_f32_16x16x32_bf16 v[34:37], v[174:177], v[190:193], v[34:37]
	v_mfma_f32_16x16x32_bf16 v[22:25], v[158:161], v[198:201], v[22:25]
	v_mfma_f32_16x16x32_bf16 v[16:19], v[174:177], v[198:201], v[16:19]
	v_mfma_f32_16x16x32_bf16 v[4:7], v[158:161], v[206:209], v[4:7]
	v_mfma_f32_16x16x32_bf16 v[0:3], v[174:177], v[206:209], v[0:3]
	v_mfma_f32_16x16x32_bf16 v[54:57], v[170:173], v[186:189], v[54:57]
	v_mfma_f32_16x16x32_bf16 v[50:53], v[178:181], v[186:189], v[50:53]
	v_mfma_f32_16x16x32_bf16 v[38:41], v[170:173], v[194:197], v[38:41]
	v_mfma_f32_16x16x32_bf16 v[34:37], v[178:181], v[194:197], v[34:37]
	v_mfma_f32_16x16x32_bf16 v[22:25], v[170:173], v[202:205], v[22:25]
	v_mfma_f32_16x16x32_bf16 v[16:19], v[178:181], v[202:205], v[16:19]
	v_mfma_f32_16x16x32_bf16 v[4:7], v[170:173], v[210:213], v[4:7]
	v_mfma_f32_16x16x32_bf16 v[0:3], v[178:181], v[210:213], v[0:3]
	s_barrier
	s_setprio 0
	s_add_i32 s95, s95, 2
	s_add_u32 s6, s6, 0x100
	s_addc_u32 s7, s7, 0
	s_add_u32 s87, s87, 0x100
	s_addc_u32 s90, s90, 0
	s_cmp_gt_u32 s95, 29

; #define PG8_STAGE(bufoff, gbase, voff) do { _Pragma("unroll") for (int _i = 0; _i < 2; ++_i) \
;         __builtin_amdgcn_global_load_lds((const unsigned*)((const char*)(gbase) + (voff)[_i]), (PG8_LAS unsigned*)(lds + (bufoff) + ldsw + _i * 8192), 16, 0, 0); } while (0)
; #define PG8_LDA(dst, b, h) do { _Pragma("unroll") for (int m = 0; m < 4; ++m) _Pragma("unroll") for (int k = 0; k < 2; ++k) dst[m][k] = *(const PG8_LAS bf16x8*)(lds + PG8_SA(b, h) + aoff + m * 2048 + k * 1024); } while (0)
; #define PG8_LDB(dst, b, h) do { _Pragma("unroll") for (int n = 0; n < 2; ++n) _Pragma("unroll") for (int k = 0; k < 2; ++k) dst[n][k] = *(const PG8_LAS bf16x8*)(lds + PG8_SB(b, h) + boff + n * 2048 + k * 1024); } while (0)
; template <class Epi, class Sched, bool ALIGN_EPI = false, bool SP2 = false>
; __device__ __forceinline__ void gemm_phase(PG8_LAS unsigned char* lds, const Gemm g, const Sched& S, const Epi& E, int tid_in) {
;     ...
;         const bool has_next = S.next(ui + 1, nxt);
;         const char* nA = has_next ? (const char*)g.A + (size_t)nxt.pm * tstep : cA; const char* nB = has_next ? (const char*)g.Bt + (size_t)nxt.pn * tstep : cB;
;         for (int t = 0; t < nt; t += 2) {
;             const bool last = (t == nt - 2);
;             const char* a1 = cA + (size_t)(t + 1) * kstep;
;             const char* a2 = last ? nA : cA + (size_t)(t + 2) * kstep; const char* b2 = last ? nB : cB + (size_t)(t + 2) * kstep;
;             const char* a3 = a2 + kstep; const char* b3 = b2 + kstep;
;             if (last && has_next) S.a_ready(nxt);
;             if constexpr (SP2) {
;             PG8_LDB(B0, 0, 0); PG8_LDB(B1, 0, 1); PG8_SCHED; PG8_LDA(At, 0, 0); PG8_STAGE(PG8_SA(1, 1), a1 + hstep, voffA);
;             PG8_WAIT_V(8); PG8_WAIT_L(0); PG8_BAR; PG8_MMA(0, 0, At, B0); PG8_MMA(0, 1, At, B1); PG8_BAR; PG8_SCHED;
;             PG8_LDA(At, 0, 1); PG8_STAGE(PG8_SB(0, 0), b2, voffB); PG8_STAGE(PG8_SB(0, 1), b2 + hstep, voffB); PG8_STAGE(PG8_SA(0, 0), a2, voffA);
;             PG8_WAIT_V(8); PG8_WAIT_L(0); PG8_BAR; PG8_MMA(1, 0, At, B0); PG8_MMA(1, 1, At, B1); PG8_BAR; PG8_SCHED;
;     ...
; #pragma unroll
;         for (int a = 0; a < 2; ++a)
; #pragma unroll
;             for (int b = 0; b < 2; ++b)
; #pragma unroll
;                 for (int m = 0; m < 4; ++m)
; #pragma unroll
;                     for (int n = 0; n < 2; ++n) acc[a][b][m][n] = (f32x4){0.f, 0.f, 0.f, 0.f};
.LBB0_501:
	s_ashr_i32 s61, s60, 31
	s_lshl_b64 s[62:63], s[60:61], 20
	s_add_u32 s62, s15, s62
	s_addc_u32 s63, s16, s63
	s_and_b64 s[64:65], s[4:5], exec
	s_cselect_b32 s7, s63, s9
	s_cselect_b32 s18, s62, s8
	s_ashr_i32 s59, s58, 31
	s_lshl_b64 s[64:65], s[58:59], 20
	s_add_u32 s64, s26, s64
	s_addc_u32 s65, s27, s65
	s_and_b64 s[70:71], s[4:5], exec
	s_cselect_b32 s59, s65, s69
	s_cselect_b32 s61, s64, s68
	s_add_u32 s8, s8, 0x80080
	s_addc_u32 s9, s9, 0
	s_add_u32 s67, s68, 0x100
	s_addc_u32 s78, s69, 0
	s_mov_b32 s79, -2
	s_add_u32 s24, s8, 0xfff80080
	s_addc_u32 s25, s9, -1
	s_add_i32 s80, 0, 0x10000
	s_cmp_eq_u32 s79, 28
	s_cselect_b32 s71, s7, s25
	s_cselect_b32 s70, s18, s24
	s_cselect_b32 s69, s59, s78
	s_cselect_b32 s68, s61, s67
	s_add_i32 s24, 0, 0x14000
	v_add_u32_e32 v110, s80, v21
	v_add_u32_e32 v158, s24, v21
	ds_read_b128 v[74:77], v110
	ds_read_b128 v[94:97], v110 offset:1024
	ds_read_b128 v[102:105], v110 offset:2048
	ds_read_b128 v[110:113], v110 offset:3072
	ds_read_b128 v[122:125], v158
	ds_read_b128 v[138:141], v158 offset:1024
	ds_read_b128 v[146:149], v158 offset:2048
	ds_read_b128 v[158:161], v158 offset:3072
	v_lshl_add_u64 v[194:195], s[8:9], 0, v[226:227]
	s_add_i32 m0, s34, 0xc000
	ds_read_b128 v[162:165], v254
	ds_read_b128 v[166:169], v254 offset:1024
	ds_read_b128 v[170:173], v254 offset:2048
	ds_read_b128 v[174:177], v254 offset:3072
	ds_read_b128 v[178:181], v254 offset:4096
	ds_read_b128 v[182:185], v254 offset:5120
	ds_read_b128 v[186:189], v254 offset:6144
	ds_read_b128 v[190:193], v254 offset:7168
	global_load_lds_dwordx4 v[194:195], off
	v_lshl_add_u64 v[194:195], s[8:9], 0, v[228:229]
	s_add_i32 m0, s34, 0xe000
	s_nop 0
	global_load_lds_dwordx4 v[194:195], off
	s_waitcnt vmcnt(8)
	s_waitcnt lgkmcnt(0)
	s_setprio 1
	s_barrier
	v_mfma_f32_16x16x32_bf16 v[154:157], v[74:77], v[162:165], 0
	v_mfma_f32_16x16x32_bf16 v[150:153], v[102:105], v[162:165], 0
	v_mfma_f32_16x16x32_bf16 v[130:133], v[74:77], v[170:173], 0
	v_mfma_f32_16x16x32_bf16 v[126:129], v[102:105], v[170:173], 0
	v_mfma_f32_16x16x32_bf16 v[106:109], v[74:77], v[178:181], 0
	v_mfma_f32_16x16x32_bf16 v[98:101], v[102:105], v[178:181], 0
	v_mfma_f32_16x16x32_bf16 v[82:85], v[74:77], v[186:189], 0
	v_mfma_f32_16x16x32_bf16 v[78:81], v[102:105], v[186:189], 0
	v_mfma_f32_16x16x32_bf16 v[154:157], v[94:97], v[166:169], v[154:157]
	v_mfma_f32_16x16x32_bf16 v[150:153], v[110:113], v[166:169], v[150:153]
	v_mfma_f32_16x16x32_bf16 v[130:133], v[94:97], v[174:177], v[130:133]
	v_mfma_f32_16x16x32_bf16 v[126:129], v[110:113], v[174:177], v[126:129]
	v_mfma_f32_16x16x32_bf16 v[106:109], v[94:97], v[182:185], v[106:109]
	v_mfma_f32_16x16x32_bf16 v[98:101], v[110:113], v[182:185], v[98:101]
	v_mfma_f32_16x16x32_bf16 v[82:85], v[94:97], v[190:193], v[82:85]
	v_mfma_f32_16x16x32_bf16 v[78:81], v[110:113], v[190:193], v[78:81]
	v_mfma_f32_16x16x32_bf16 v[142:145], v[122:125], v[162:165], 0
	v_mfma_f32_16x16x32_bf16 v[134:137], v[146:149], v[162:165], 0
	v_mfma_f32_16x16x32_bf16 v[118:121], v[122:125], v[170:173], 0
	v_mfma_f32_16x16x32_bf16 v[114:117], v[146:149], v[170:173], 0
	v_mfma_f32_16x16x32_bf16 v[90:93], v[122:125], v[178:181], 0
	v_mfma_f32_16x16x32_bf16 v[86:89], v[146:149], v[178:181], 0
	v_mfma_f32_16x16x32_bf16 v[70:73], v[122:125], v[186:189], 0
	v_mfma_f32_16x16x32_bf16 v[66:69], v[146:149], v[186:189], 0
	v_mfma_f32_16x16x32_bf16 v[142:145], v[138:141], v[166:169], v[142:145]
	v_mfma_f32_16x16x32_bf16 v[134:137], v[158:161], v[166:169], v[134:137]
	v_mfma_f32_16x16x32_bf16 v[118:121], v[138:141], v[174:177], v[118:121]
	v_mfma_f32_16x16x32_bf16 v[114:117], v[158:161], v[174:177], v[114:117]
	v_mfma_f32_16x16x32_bf16 v[90:93], v[138:141], v[182:185], v[90:93]
	v_mfma_f32_16x16x32_bf16 v[86:89], v[158:161], v[182:185], v[86:89]
	v_mfma_f32_16x16x32_bf16 v[70:73], v[138:141], v[190:193], v[70:73]
	v_mfma_f32_16x16x32_bf16 v[66:69], v[158:161], v[190:193], v[66:69]
	s_barrier
	s_setprio 0
	s_add_i32 s25, s80, s14
	v_lshl_add_u64 v[194:195], s[68:69], 0, v[220:221]
	s_mov_b32 m0, s25
	ds_read_b128 v[162:165], v254 offset:16384
	ds_read_b128 v[166:169], v254 offset:17408
	ds_read_b128 v[170:173], v254 offset:18432
	ds_read_b128 v[174:177], v254 offset:19456
	ds_read_b128 v[178:181], v254 offset:20480
	ds_read_b128 v[182:185], v254 offset:21504
	ds_read_b128 v[186:189], v254 offset:22528
	ds_read_b128 v[190:193], v254 offset:23552
	global_load_lds_dwordx4 v[194:195], off
	s_add_i32 m0, s25, 0x2000
	s_add_u32 s80, s68, 0x80000
	v_lshl_add_u64 v[196:197], s[68:69], 0, v[224:225]
	s_addc_u32 s81, s69, 0
	s_add_i32 s24, s24, s14
	global_load_lds_dwordx4 v[196:197], off
	v_lshl_add_u64 v[198:199], s[80:81], 0, v[220:221]
	s_mov_b32 m0, s24
	v_lshl_add_u64 v[200:201], s[70:71], 0, v[222:223]
	global_load_lds_dwordx4 v[198:199], off
	v_lshl_add_u64 v[198:199], s[80:81], 0, v[224:225]
	s_add_i32 m0, s24, 0x2000
	s_nop 0
	global_load_lds_dwordx4 v[198:199], off
	v_lshl_add_u64 v[198:199], s[70:71], 0, v[218:219]
	s_mov_b32 m0, s34
	s_nop 0
	global_load_lds_dwordx4 v[198:199], off
	s_mov_b32 m0, s35
	s_nop 0
	global_load_lds_dwordx4 v[200:201], off
	s_waitcnt vmcnt(8)
	s_waitcnt lgkmcnt(0)
	s_setprio 1
	s_barrier
; #define PG8_STAGE(bufoff, gbase, voff) do { _Pragma("unroll") for (int _i = 0; _i < 2; ++_i) \
;         __builtin_amdgcn_global_load_lds((const unsigned*)((const char*)(gbase) + (voff)[_i]), (PG8_LAS unsigned*)(lds + (bufoff) + ldsw + _i * 8192), 16, 0, 0); } while (0)
; #define PG8_LDA(dst, b, h) do { _Pragma("unroll") for (int m = 0; m < 4; ++m) _Pragma("unroll") for (int k = 0; k < 2; ++k) dst[m][k] = *(const PG8_LAS bf16x8*)(lds + PG8_SA(b, h) + aoff + m * 2048 + k * 1024); } while (0)
; #define PG8_LDB(dst, b, h) do { _Pragma("unroll") for (int n = 0; n < 2; ++n) _Pragma("unroll") for (int k = 0; k < 2; ++k) dst[n][k] = *(const PG8_LAS bf16x8*)(lds + PG8_SB(b, h) + boff + n * 2048 + k * 1024); } while (0)
; #define PG8_MMA(ai, bj, At, Bt) do { __builtin_amdgcn_s_setprio(1); _Pragma("unroll") for (int m = 0; m < 4; ++m) _Pragma("unroll") for (int n = 0; n < 2; ++n) _Pragma("unroll") for (int k = 0; k < 2; ++k) \
;         acc[ai][bj][m][n] = __builtin_amdgcn_mfma_f32_16x16x32_bf16(Bt[n][k], At[m][k], acc[ai][bj][m][n], 0, 0, 0); __builtin_amdgcn_s_setprio(0); } while (0)
; #define PG8_WAIT_V(n) asm volatile("s_waitcnt vmcnt(" #n ")" ::: "memory")
; #define PG8_WAIT_L(n) asm volatile("s_waitcnt lgkmcnt(" #n ")" ::: "memory")
; #define PG8_BAR __builtin_amdgcn_s_barrier()
; #define PG8_SCHED __builtin_amdgcn_sched_barrier(0)
; template <class Epi, class Sched, bool ALIGN_EPI = false, bool SP2 = false>
; __device__ __forceinline__ void gemm_phase(PG8_LAS unsigned char* lds, const Gemm g, const Sched& S, const Epi& E, int tid_in) {
;     ...
;             PG8_WAIT_V(8); PG8_WAIT_L(0); PG8_BAR; PG8_MMA(1, 0, At, B0); PG8_MMA(1, 1, At, B1); PG8_BAR; PG8_SCHED;
;             PG8_LDB(B0, 1, 0); PG8_LDB(B1, 1, 1); PG8_SCHED; PG8_LDA(At, 1, 0); PG8_STAGE(PG8_SA(0, 1), a2 + hstep, voffA);
;             PG8_WAIT_V(8); PG8_WAIT_L(0); PG8_BAR; PG8_MMA(0, 0, At, B0); PG8_MMA(0, 1, At, B1); PG8_BAR; PG8_SCHED;
	v_mfma_f32_16x16x32_bf16 v[62:65], v[74:77], v[162:165], 0
	v_mfma_f32_16x16x32_bf16 v[58:61], v[102:105], v[162:165], 0
	v_mfma_f32_16x16x32_bf16 v[46:49], v[74:77], v[170:173], 0
	v_mfma_f32_16x16x32_bf16 v[42:45], v[102:105], v[170:173], 0
	v_mfma_f32_16x16x32_bf16 v[30:33], v[74:77], v[178:181], 0
	v_mfma_f32_16x16x32_bf16 v[26:29], v[102:105], v[178:181], 0
	v_mfma_f32_16x16x32_bf16 v[12:15], v[74:77], v[186:189], 0
	v_mfma_f32_16x16x32_bf16 v[8:11], v[102:105], v[186:189], 0
	v_mfma_f32_16x16x32_bf16 v[62:65], v[94:97], v[166:169], v[62:65]
	v_mfma_f32_16x16x32_bf16 v[58:61], v[110:113], v[166:169], v[58:61]
	v_mfma_f32_16x16x32_bf16 v[46:49], v[94:97], v[174:177], v[46:49]
	v_mfma_f32_16x16x32_bf16 v[42:45], v[110:113], v[174:177], v[42:45]
	v_mfma_f32_16x16x32_bf16 v[30:33], v[94:97], v[182:185], v[30:33]
	v_mfma_f32_16x16x32_bf16 v[26:29], v[110:113], v[182:185], v[26:29]
	v_mfma_f32_16x16x32_bf16 v[12:15], v[94:97], v[190:193], v[12:15]
	v_mfma_f32_16x16x32_bf16 v[8:11], v[110:113], v[190:193], v[8:11]
	v_mfma_f32_16x16x32_bf16 v[54:57], v[122:125], v[162:165], 0
	v_mfma_f32_16x16x32_bf16 v[50:53], v[146:149], v[162:165], 0
	v_mfma_f32_16x16x32_bf16 v[38:41], v[122:125], v[170:173], 0
	v_mfma_f32_16x16x32_bf16 v[34:37], v[146:149], v[170:173], 0
	v_mfma_f32_16x16x32_bf16 v[22:25], v[122:125], v[178:181], 0
	v_mfma_f32_16x16x32_bf16 v[16:19], v[146:149], v[178:181], 0
	v_mfma_f32_16x16x32_bf16 v[4:7], v[122:125], v[186:189], 0
	v_mfma_f32_16x16x32_bf16 v[0:3], v[146:149], v[186:189], 0
	v_mfma_f32_16x16x32_bf16 v[54:57], v[138:141], v[166:169], v[54:57]
	v_mfma_f32_16x16x32_bf16 v[50:53], v[158:161], v[166:169], v[50:53]
	v_mfma_f32_16x16x32_bf16 v[38:41], v[138:141], v[174:177], v[38:41]
	v_mfma_f32_16x16x32_bf16 v[34:37], v[158:161], v[174:177], v[34:37]
	v_mfma_f32_16x16x32_bf16 v[22:25], v[138:141], v[182:185], v[22:25]
	v_mfma_f32_16x16x32_bf16 v[16:19], v[158:161], v[182:185], v[16:19]
	v_mfma_f32_16x16x32_bf16 v[4:7], v[138:141], v[190:193], v[4:7]
	v_mfma_f32_16x16x32_bf16 v[0:3], v[158:161], v[190:193], v[0:3]
	s_barrier
	s_setprio 0
	s_add_i32 s24, 0, 0x18000
	s_add_i32 s25, 0, 0x1c000
	v_add_u32_e32 v110, s24, v21
	v_add_u32_e32 v158, s25, v21
	ds_read_b128 v[74:77], v110
	ds_read_b128 v[94:97], v110 offset:1024
	ds_read_b128 v[102:105], v110 offset:2048
	ds_read_b128 v[110:113], v110 offset:3072
	ds_read_b128 v[122:125], v158
	ds_read_b128 v[138:141], v158 offset:1024
	ds_read_b128 v[146:149], v158 offset:2048
	ds_read_b128 v[158:161], v158 offset:3072
	s_add_u32 s70, s70, 0x80000
	s_addc_u32 s71, s71, 0
	s_mov_b32 m0, s37
	v_lshl_add_u64 v[202:203], s[70:71], 0, v[218:219]
	ds_read_b128 v[162:165], v254 offset:32768
	ds_read_b128 v[166:169], v254 offset:33792
	ds_read_b128 v[170:173], v254 offset:34816
	ds_read_b128 v[174:177], v254 offset:35840
	ds_read_b128 v[178:181], v254 offset:36864
	ds_read_b128 v[182:185], v254 offset:37888
	ds_read_b128 v[186:189], v254 offset:38912
	ds_read_b128 v[190:193], v254 offset:39936
	global_load_lds_dwordx4 v[202:203], off
	v_lshl_add_u64 v[202:203], s[70:71], 0, v[222:223]
	s_mov_b32 m0, s38
	s_nop 0
	global_load_lds_dwordx4 v[202:203], off
	s_waitcnt vmcnt(8)
	s_waitcnt lgkmcnt(0)
	s_setprio 1
	s_barrier
	v_mfma_f32_16x16x32_bf16 v[154:157], v[74:77], v[162:165], v[154:157]
	v_mfma_f32_16x16x32_bf16 v[150:153], v[102:105], v[162:165], v[150:153]
	v_mfma_f32_16x16x32_bf16 v[130:133], v[74:77], v[170:173], v[130:133]
	v_mfma_f32_16x16x32_bf16 v[126:129], v[102:105], v[170:173], v[126:129]
	v_mfma_f32_16x16x32_bf16 v[106:109], v[74:77], v[178:181], v[106:109]
	v_mfma_f32_16x16x32_bf16 v[98:101], v[102:105], v[178:181], v[98:101]
	v_mfma_f32_16x16x32_bf16 v[82:85], v[74:77], v[186:189], v[82:85]
	v_mfma_f32_16x16x32_bf16 v[78:81], v[102:105], v[186:189], v[78:81]
	v_mfma_f32_16x16x32_bf16 v[154:157], v[94:97], v[166:169], v[154:157]
	v_mfma_f32_16x16x32_bf16 v[150:153], v[110:113], v[166:169], v[150:153]
	v_mfma_f32_16x16x32_bf16 v[130:133], v[94:97], v[174:177], v[130:133]
	v_mfma_f32_16x16x32_bf16 v[126:129], v[110:113], v[174:177], v[126:129]
	v_mfma_f32_16x16x32_bf16 v[106:109], v[94:97], v[182:185], v[106:109]
	v_mfma_f32_16x16x32_bf16 v[98:101], v[110:113], v[182:185], v[98:101]
	v_mfma_f32_16x16x32_bf16 v[82:85], v[94:97], v[190:193], v[82:85]
	v_mfma_f32_16x16x32_bf16 v[78:81], v[110:113], v[190:193], v[78:81]
	v_mfma_f32_16x16x32_bf16 v[142:145], v[122:125], v[162:165], v[142:145]
	v_mfma_f32_16x16x32_bf16 v[134:137], v[146:149], v[162:165], v[134:137]
	v_mfma_f32_16x16x32_bf16 v[118:121], v[122:125], v[170:173], v[118:121]
	v_mfma_f32_16x16x32_bf16 v[114:117], v[146:149], v[170:173], v[114:117]
	v_mfma_f32_16x16x32_bf16 v[90:93], v[122:125], v[178:181], v[90:93]
	v_mfma_f32_16x16x32_bf16 v[86:89], v[146:149], v[178:181], v[86:89]
	v_mfma_f32_16x16x32_bf16 v[70:73], v[122:125], v[186:189], v[70:73]
	v_mfma_f32_16x16x32_bf16 v[66:69], v[146:149], v[186:189], v[66:69]
	v_mfma_f32_16x16x32_bf16 v[142:145], v[138:141], v[166:169], v[142:145]
	v_mfma_f32_16x16x32_bf16 v[134:137], v[158:161], v[166:169], v[134:137]
	v_mfma_f32_16x16x32_bf16 v[118:121], v[138:141], v[174:177], v[118:121]
	v_mfma_f32_16x16x32_bf16 v[114:117], v[158:161], v[174:177], v[114:117]
	v_mfma_f32_16x16x32_bf16 v[90:93], v[138:141], v[182:185], v[90:93]
	v_mfma_f32_16x16x32_bf16 v[86:89], v[158:161], v[182:185], v[86:89]
	v_mfma_f32_16x16x32_bf16 v[70:73], v[138:141], v[190:193], v[70:73]
	v_mfma_f32_16x16x32_bf16 v[66:69], v[158:161], v[190:193], v[66:69]
	s_barrier
; #define PG8_STAGE(bufoff, gbase, voff) do { _Pragma("unroll") for (int _i = 0; _i < 2; ++_i) \
;         __builtin_amdgcn_global_load_lds((const unsigned*)((const char*)(gbase) + (voff)[_i]), (PG8_LAS unsigned*)(lds + (bufoff) + ldsw + _i * 8192), 16, 0, 0); } while (0)
; #define PG8_LDA(dst, b, h) do { _Pragma("unroll") for (int m = 0; m < 4; ++m) _Pragma("unroll") for (int k = 0; k < 2; ++k) dst[m][k] = *(const PG8_LAS bf16x8*)(lds + PG8_SA(b, h) + aoff + m * 2048 + k * 1024); } while (0)
; #define PG8_MMA(ai, bj, At, Bt) do { __builtin_amdgcn_s_setprio(1); _Pragma("unroll") for (int m = 0; m < 4; ++m) _Pragma("unroll") for (int n = 0; n < 2; ++n) _Pragma("unroll") for (int k = 0; k < 2; ++k) \
;         acc[ai][bj][m][n] = __builtin_amdgcn_mfma_f32_16x16x32_bf16(Bt[n][k], At[m][k], acc[ai][bj][m][n], 0, 0, 0); __builtin_amdgcn_s_setprio(0); } while (0)
; #define PG8_WAIT_V(n) asm volatile("s_waitcnt vmcnt(" #n ")" ::: "memory")
; #define PG8_WAIT_L(n) asm volatile("s_waitcnt lgkmcnt(" #n ")" ::: "memory")
; #define PG8_BAR __builtin_amdgcn_s_barrier()
; #define PG8_SCHED __builtin_amdgcn_sched_barrier(0)
; template <class Epi, class Sched, bool ALIGN_EPI = false, bool SP2 = false>
; __device__ __forceinline__ void gemm_phase(PG8_LAS unsigned char* lds, const Gemm g, const Sched& S, const Epi& E, int tid_in) {
;     ...
;             PG8_LDA(At, 1, 1); PG8_STAGE(PG8_SB(1, 0), b3, voffB); PG8_STAGE(PG8_SB(1, 1), b3 + hstep, voffB); PG8_STAGE(PG8_SA(1, 0), a3, voffA);
;             PG8_WAIT_V(8); PG8_WAIT_L(0); PG8_BAR; PG8_MMA(1, 0, At, B0); PG8_MMA(1, 1, At, B1); PG8_BAR; PG8_SCHED;
	s_setprio 0
	s_add_i32 s24, s24, s14
	v_lshl_add_u64 v[194:195], v[194:195], 0, s[22:23]
	s_mov_b32 m0, s24
	ds_read_b128 v[162:165], v254 offset:49152
	ds_read_b128 v[166:169], v254 offset:50176
	ds_read_b128 v[170:173], v254 offset:51200
	ds_read_b128 v[174:177], v254 offset:52224
	ds_read_b128 v[178:181], v254 offset:53248
	ds_read_b128 v[182:185], v254 offset:54272
	ds_read_b128 v[186:189], v254 offset:55296
	ds_read_b128 v[190:193], v254 offset:56320
	global_load_lds_dwordx4 v[194:195], off
	s_add_i32 m0, s24, 0x2000
	s_add_u32 s68, s68, 0x80080
	v_lshl_add_u64 v[194:195], v[196:197], 0, s[22:23]
	s_addc_u32 s69, s69, 0
	s_add_i32 s24, s25, s14
	global_load_lds_dwordx4 v[194:195], off
	v_lshl_add_u64 v[194:195], s[68:69], 0, v[220:221]
	s_mov_b32 m0, s24
	s_nop 0
	global_load_lds_dwordx4 v[194:195], off
	v_lshl_add_u64 v[194:195], s[68:69], 0, v[224:225]
	s_add_i32 m0, s24, 0x2000
	s_nop 0
	global_load_lds_dwordx4 v[194:195], off
	v_lshl_add_u64 v[194:195], v[198:199], 0, s[22:23]
	s_mov_b32 m0, s73
	s_nop 0
	global_load_lds_dwordx4 v[194:195], off
	v_lshl_add_u64 v[194:195], v[200:201], 0, s[22:23]
	s_mov_b32 m0, s74
	s_nop 0
	global_load_lds_dwordx4 v[194:195], off
	s_waitcnt vmcnt(8)
	s_waitcnt lgkmcnt(0)
	s_setprio 1
	s_barrier
	v_mfma_f32_16x16x32_bf16 v[62:65], v[74:77], v[162:165], v[62:65]
	v_mfma_f32_16x16x32_bf16 v[58:61], v[102:105], v[162:165], v[58:61]
	v_mfma_f32_16x16x32_bf16 v[46:49], v[74:77], v[170:173], v[46:49]
	v_mfma_f32_16x16x32_bf16 v[42:45], v[102:105], v[170:173], v[42:45]
	v_mfma_f32_16x16x32_bf16 v[30:33], v[74:77], v[178:181], v[30:33]
	v_mfma_f32_16x16x32_bf16 v[26:29], v[102:105], v[178:181], v[26:29]
	v_mfma_f32_16x16x32_bf16 v[12:15], v[74:77], v[186:189], v[12:15]
	v_mfma_f32_16x16x32_bf16 v[8:11], v[102:105], v[186:189], v[8:11]
	v_mfma_f32_16x16x32_bf16 v[62:65], v[94:97], v[166:169], v[62:65]
	v_mfma_f32_16x16x32_bf16 v[58:61], v[110:113], v[166:169], v[58:61]
	v_mfma_f32_16x16x32_bf16 v[46:49], v[94:97], v[174:177], v[46:49]
	v_mfma_f32_16x16x32_bf16 v[42:45], v[110:113], v[174:177], v[42:45]
	v_mfma_f32_16x16x32_bf16 v[30:33], v[94:97], v[182:185], v[30:33]
	v_mfma_f32_16x16x32_bf16 v[26:29], v[110:113], v[182:185], v[26:29]
	v_mfma_f32_16x16x32_bf16 v[12:15], v[94:97], v[190:193], v[12:15]
	v_mfma_f32_16x16x32_bf16 v[8:11], v[110:113], v[190:193], v[8:11]
	v_mfma_f32_16x16x32_bf16 v[54:57], v[122:125], v[162:165], v[54:57]
	v_mfma_f32_16x16x32_bf16 v[50:53], v[146:149], v[162:165], v[50:53]
	v_mfma_f32_16x16x32_bf16 v[38:41], v[122:125], v[170:173], v[38:41]
	v_mfma_f32_16x16x32_bf16 v[34:37], v[146:149], v[170:173], v[34:37]
	v_mfma_f32_16x16x32_bf16 v[22:25], v[122:125], v[178:181], v[22:25]
	v_mfma_f32_16x16x32_bf16 v[16:19], v[146:149], v[178:181], v[16:19]
	v_mfma_f32_16x16x32_bf16 v[4:7], v[122:125], v[186:189], v[4:7]
	v_mfma_f32_16x16x32_bf16 v[0:3], v[146:149], v[186:189], v[0:3]
	v_mfma_f32_16x16x32_bf16 v[54:57], v[138:141], v[166:169], v[54:57]
	v_mfma_f32_16x16x32_bf16 v[50:53], v[158:161], v[166:169], v[50:53]
	v_mfma_f32_16x16x32_bf16 v[38:41], v[138:141], v[174:177], v[38:41]
	v_mfma_f32_16x16x32_bf16 v[34:37], v[158:161], v[174:177], v[34:37]
	v_mfma_f32_16x16x32_bf16 v[22:25], v[138:141], v[182:185], v[22:25]
	v_mfma_f32_16x16x32_bf16 v[16:19], v[158:161], v[182:185], v[16:19]
	v_mfma_f32_16x16x32_bf16 v[4:7], v[138:141], v[190:193], v[4:7]
	v_mfma_f32_16x16x32_bf16 v[0:3], v[158:161], v[190:193], v[0:3]
	s_barrier
	s_setprio 0
	s_add_i32 s79, s79, 2
	s_add_u32 s8, s8, 0x100
	s_addc_u32 s9, s9, 0
	s_add_u32 s67, s67, 0x100
	s_addc_u32 s78, s78, 0
	s_cmp_gt_u32 s79, 29

; #define PG8_STAGE(bufoff, gbase, voff) do { _Pragma("unroll") for (int _i = 0; _i < 2; ++_i) \
;         __builtin_amdgcn_global_load_lds((const unsigned*)((const char*)(gbase) + (voff)[_i]), (PG8_LAS unsigned*)(lds + (bufoff) + ldsw + _i * 8192), 16, 0, 0); } while (0)
; #define PG8_LDA(dst, b, h) do { _Pragma("unroll") for (int m = 0; m < 4; ++m) _Pragma("unroll") for (int k = 0; k < 2; ++k) dst[m][k] = *(const PG8_LAS bf16x8*)(lds + PG8_SA(b, h) + aoff + m * 2048 + k * 1024); } while (0)
; #define PG8_LDB(dst, b, h) do { _Pragma("unroll") for (int n = 0; n < 2; ++n) _Pragma("unroll") for (int k = 0; k < 2; ++k) dst[n][k] = *(const PG8_LAS bf16x8*)(lds + PG8_SB(b, h) + boff + n * 2048 + k * 1024); } while (0)
; template <class Epi, class Sched, bool ALIGN_EPI = false, bool SP2 = false>
; __device__ __forceinline__ void gemm_phase(PG8_LAS unsigned char* lds, const Gemm g, const Sched& S, const Epi& E, int tid_in) {
;     ...
;         const bool has_next = S.next(ui + 1, nxt);
;         const char* nA = has_next ? (const char*)g.A + (size_t)nxt.pm * tstep : cA; const char* nB = has_next ? (const char*)g.Bt + (size_t)nxt.pn * tstep : cB;
;         for (int t = 0; t < nt; t += 2) {
;             const bool last = (t == nt - 2);
;             const char* a1 = cA + (size_t)(t + 1) * kstep;
;             const char* a2 = last ? nA : cA + (size_t)(t + 2) * kstep; const char* b2 = last ? nB : cB + (size_t)(t + 2) * kstep;
;             const char* a3 = a2 + kstep; const char* b3 = b2 + kstep;
;             if (last && has_next) S.a_ready(nxt);
;             if constexpr (SP2) {
;             PG8_LDB(B0, 0, 0); PG8_LDB(B1, 0, 1); PG8_SCHED; PG8_LDA(At, 0, 0); PG8_STAGE(PG8_SA(1, 1), a1 + hstep, voffA);
;             PG8_WAIT_V(8); PG8_WAIT_L(0); PG8_BAR; PG8_MMA(0, 0, At, B0); PG8_MMA(0, 1, At, B1); PG8_BAR; PG8_SCHED;
;             PG8_LDA(At, 0, 1); PG8_STAGE(PG8_SB(0, 0), b2, voffB); PG8_STAGE(PG8_SB(0, 1), b2 + hstep, voffB); PG8_STAGE(PG8_SA(0, 0), a2, voffA);
;             PG8_WAIT_V(8); PG8_WAIT_L(0); PG8_BAR; PG8_MMA(1, 0, At, B0); PG8_MMA(1, 1, At, B1); PG8_BAR; PG8_SCHED;
;     ...
; #pragma unroll
;         for (int a = 0; a < 2; ++a)
; #pragma unroll
;             for (int b = 0; b < 2; ++b)
; #pragma unroll
;                 for (int m = 0; m < 4; ++m)
; #pragma unroll
;                     for (int n = 0; n < 2; ++n) acc[a][b][m][n] = (f32x4){0.f, 0.f, 0.f, 0.f};
.LBB0_715:
	s_ashr_i32 s71, s70, 31
	s_lshl_b64 s[6:7], s[70:71], 20
	s_add_u32 s72, s45, s6
	s_addc_u32 s73, s82, s7
	s_and_b64 s[6:7], s[4:5], exec
	s_cselect_b32 s9, s73, s79
	s_cselect_b32 s71, s72, s78
	s_ashr_i32 s69, s68, 31
	s_lshl_b64 s[6:7], s[68:69], 20
	s_add_u32 s74, s83, s6
	s_addc_u32 s75, s84, s7
	s_and_b64 s[6:7], s[4:5], exec
	s_cselect_b32 s69, s75, s11
	s_cselect_b32 s77, s74, s10
	s_add_u32 s6, s78, 0x80080
	s_addc_u32 s7, s79, 0
	s_add_u32 s80, s10, 0x100
	s_addc_u32 s81, s11, 0
	s_mov_b32 vcc_lo, -2
	s_lshl_b32 s98, s8, 10
	s_lshr_b32 s99, s3, 2
	s_lshl_b32 s99, s99, 8
	s_add_u32 s98, s98, s99
	s_add_u32 s100, s58, s98
	s_addc_u32 s101, s59, 0
	v_and_b32_e32 v243, 15, v250
	v_lshlrev_b32_e32 v243, 4, v243
	global_load_dwordx4 v[236:239], v243, s[100:101]
	global_load_dwordx4 v[240:243], v243, s[100:101] offset:512
	s_add_u32 s10, s6, 0xfff80080
	s_addc_u32 s11, s7, -1
	s_add_i32 s24, 0, 0x10000
	s_cmp_eq_u32 vcc_lo, 28
	s_cselect_b32 s79, s9, s11
	s_cselect_b32 s78, s71, s10
	s_cselect_b32 s11, s69, s81
	s_cselect_b32 s10, s77, s80
	s_add_i32 vcc_hi, 0, 0x14000
	v_add_u32_e32 v142, s24, v21
	v_add_u32_e32 v158, vcc_hi, v21
	ds_read_b128 v[130:133], v142
	ds_read_b128 v[134:137], v142 offset:1024
	ds_read_b128 v[138:141], v142 offset:2048
	ds_read_b128 v[142:145], v142 offset:3072
	ds_read_b128 v[146:149], v158
	ds_read_b128 v[150:153], v158 offset:1024
	ds_read_b128 v[154:157], v158 offset:2048
	ds_read_b128 v[158:161], v158 offset:3072
	v_lshl_add_u64 v[206:207], s[6:7], 0, v[178:179]
	s_add_i32 m0, s27, 0xc000
	ds_read_b128 v[162:165], v254
	ds_read_b128 v[166:169], v254 offset:1024
	ds_read_b128 v[182:185], v254 offset:2048
	ds_read_b128 v[186:189], v254 offset:3072
	ds_read_b128 v[190:193], v254 offset:4096
	ds_read_b128 v[194:197], v254 offset:5120
	ds_read_b128 v[198:201], v254 offset:6144
	ds_read_b128 v[202:205], v254 offset:7168
	global_load_lds_dwordx4 v[206:207], off
	v_lshl_add_u64 v[206:207], s[6:7], 0, v[180:181]
	s_add_i32 m0, s27, 0xe000
	s_nop 0
	global_load_lds_dwordx4 v[206:207], off
	s_waitcnt vmcnt(8)
	s_waitcnt lgkmcnt(0)
	s_setprio 1
	s_barrier
	v_mfma_f32_16x16x32_bf16 v[126:129], v[130:133], v[162:165], 0
	v_mfma_f32_16x16x32_bf16 v[82:85], v[138:141], v[162:165], 0
	v_mfma_f32_16x16x32_bf16 v[110:113], v[130:133], v[182:185], 0
	v_mfma_f32_16x16x32_bf16 v[46:49], v[138:141], v[182:185], 0
	v_mfma_f32_16x16x32_bf16 v[106:109], v[130:133], v[190:193], 0
	v_mfma_f32_16x16x32_bf16 v[42:45], v[138:141], v[190:193], 0
	v_mfma_f32_16x16x32_bf16 v[114:117], v[130:133], v[198:201], 0
	v_mfma_f32_16x16x32_bf16 v[50:53], v[138:141], v[198:201], 0
	v_mfma_f32_16x16x32_bf16 v[126:129], v[134:137], v[166:169], v[126:129]
	v_mfma_f32_16x16x32_bf16 v[82:85], v[142:145], v[166:169], v[82:85]
	v_mfma_f32_16x16x32_bf16 v[110:113], v[134:137], v[186:189], v[110:113]
	v_mfma_f32_16x16x32_bf16 v[46:49], v[142:145], v[186:189], v[46:49]
	v_mfma_f32_16x16x32_bf16 v[106:109], v[134:137], v[194:197], v[106:109]
	v_mfma_f32_16x16x32_bf16 v[42:45], v[142:145], v[194:197], v[42:45]
	v_mfma_f32_16x16x32_bf16 v[114:117], v[134:137], v[202:205], v[114:117]
	v_mfma_f32_16x16x32_bf16 v[50:53], v[142:145], v[202:205], v[50:53]
	v_mfma_f32_16x16x32_bf16 v[122:125], v[146:149], v[162:165], 0
	v_mfma_f32_16x16x32_bf16 v[78:81], v[154:157], v[162:165], 0
	v_mfma_f32_16x16x32_bf16 v[102:105], v[146:149], v[182:185], 0
	v_mfma_f32_16x16x32_bf16 v[38:41], v[154:157], v[182:185], 0
	v_mfma_f32_16x16x32_bf16 v[98:101], v[146:149], v[190:193], 0
	v_mfma_f32_16x16x32_bf16 v[34:37], v[154:157], v[190:193], 0
	v_mfma_f32_16x16x32_bf16 v[118:121], v[146:149], v[198:201], 0
	v_mfma_f32_16x16x32_bf16 v[54:57], v[154:157], v[198:201], 0
	v_mfma_f32_16x16x32_bf16 v[122:125], v[150:153], v[166:169], v[122:125]
	v_mfma_f32_16x16x32_bf16 v[78:81], v[158:161], v[166:169], v[78:81]
	v_mfma_f32_16x16x32_bf16 v[102:105], v[150:153], v[186:189], v[102:105]
	v_mfma_f32_16x16x32_bf16 v[38:41], v[158:161], v[186:189], v[38:41]
	v_mfma_f32_16x16x32_bf16 v[98:101], v[150:153], v[194:197], v[98:101]
	v_mfma_f32_16x16x32_bf16 v[34:37], v[158:161], v[194:197], v[34:37]
	v_mfma_f32_16x16x32_bf16 v[118:121], v[150:153], v[202:205], v[118:121]
	v_mfma_f32_16x16x32_bf16 v[54:57], v[158:161], v[202:205], v[54:57]
	s_barrier
	s_setprio 0
	s_add_i32 s24, s24, s85
	v_lshl_add_u64 v[206:207], s[10:11], 0, v[172:173]
	s_mov_b32 m0, s24
	ds_read_b128 v[162:165], v254 offset:16384
	ds_read_b128 v[166:169], v254 offset:17408
	ds_read_b128 v[182:185], v254 offset:18432
	ds_read_b128 v[186:189], v254 offset:19456
	ds_read_b128 v[190:193], v254 offset:20480
	ds_read_b128 v[194:197], v254 offset:21504
	ds_read_b128 v[198:201], v254 offset:22528
	ds_read_b128 v[202:205], v254 offset:23552
	global_load_lds_dwordx4 v[206:207], off
	s_add_i32 m0, s24, 0x2000
	s_add_u32 s24, s10, 0x80000
	v_lshl_add_u64 v[208:209], s[10:11], 0, v[176:177]
	s_addc_u32 s25, s11, 0
	s_add_i32 vcc_hi, vcc_hi, s85
	global_load_lds_dwordx4 v[208:209], off
	v_lshl_add_u64 v[210:211], s[24:25], 0, v[172:173]
	s_mov_b32 m0, vcc_hi
	v_lshl_add_u64 v[212:213], s[78:79], 0, v[174:175]
	global_load_lds_dwordx4 v[210:211], off
	v_lshl_add_u64 v[210:211], s[24:25], 0, v[176:177]
	s_add_i32 m0, vcc_hi, 0x2000
	s_nop 0
	global_load_lds_dwordx4 v[210:211], off
	v_lshl_add_u64 v[210:211], s[78:79], 0, v[170:171]
	s_mov_b32 m0, s27
	s_nop 0
	global_load_lds_dwordx4 v[210:211], off
	s_mov_b32 m0, s87
	s_nop 0
	global_load_lds_dwordx4 v[212:213], off
	s_waitcnt vmcnt(8)
	s_waitcnt lgkmcnt(0)
	s_setprio 1
	s_barrier
; #define PG8_STAGE(bufoff, gbase, voff) do { _Pragma("unroll") for (int _i = 0; _i < 2; ++_i) \
;         __builtin_amdgcn_global_load_lds((const unsigned*)((const char*)(gbase) + (voff)[_i]), (PG8_LAS unsigned*)(lds + (bufoff) + ldsw + _i * 8192), 16, 0, 0); } while (0)
; #define PG8_LDA(dst, b, h) do { _Pragma("unroll") for (int m = 0; m < 4; ++m) _Pragma("unroll") for (int k = 0; k < 2; ++k) dst[m][k] = *(const PG8_LAS bf16x8*)(lds + PG8_SA(b, h) + aoff + m * 2048 + k * 1024); } while (0)
; #define PG8_LDB(dst, b, h) do { _Pragma("unroll") for (int n = 0; n < 2; ++n) _Pragma("unroll") for (int k = 0; k < 2; ++k) dst[n][k] = *(const PG8_LAS bf16x8*)(lds + PG8_SB(b, h) + boff + n * 2048 + k * 1024); } while (0)
; #define PG8_MMA(ai, bj, At, Bt) do { __builtin_amdgcn_s_setprio(1); _Pragma("unroll") for (int m = 0; m < 4; ++m) _Pragma("unroll") for (int n = 0; n < 2; ++n) _Pragma("unroll") for (int k = 0; k < 2; ++k) \
;         acc[ai][bj][m][n] = __builtin_amdgcn_mfma_f32_16x16x32_bf16(Bt[n][k], At[m][k], acc[ai][bj][m][n], 0, 0, 0); __builtin_amdgcn_s_setprio(0); } while (0)
; #define PG8_WAIT_V(n) asm volatile("s_waitcnt vmcnt(" #n ")" ::: "memory")
; #define PG8_WAIT_L(n) asm volatile("s_waitcnt lgkmcnt(" #n ")" ::: "memory")
; #define PG8_BAR __builtin_amdgcn_s_barrier()
; #define PG8_SCHED __builtin_amdgcn_sched_barrier(0)
; template <class Epi, class Sched, bool ALIGN_EPI = false, bool SP2 = false>
; __device__ __forceinline__ void gemm_phase(PG8_LAS unsigned char* lds, const Gemm g, const Sched& S, const Epi& E, int tid_in) {
;     ...
;             PG8_WAIT_V(8); PG8_WAIT_L(0); PG8_BAR; PG8_MMA(1, 0, At, B0); PG8_MMA(1, 1, At, B1); PG8_BAR; PG8_SCHED;
;             PG8_LDB(B0, 1, 0); PG8_LDB(B1, 1, 1); PG8_SCHED; PG8_LDA(At, 1, 0); PG8_STAGE(PG8_SA(0, 1), a2 + hstep, voffA);
;             PG8_WAIT_V(8); PG8_WAIT_L(0); PG8_BAR; PG8_MMA(0, 0, At, B0); PG8_MMA(0, 1, At, B1); PG8_BAR; PG8_SCHED;
	v_mfma_f32_16x16x32_bf16 v[86:89], v[130:133], v[162:165], 0
	v_mfma_f32_16x16x32_bf16 v[22:25], v[138:141], v[162:165], 0
	v_mfma_f32_16x16x32_bf16 v[70:73], v[130:133], v[182:185], 0
	v_mfma_f32_16x16x32_bf16 v[12:15], v[138:141], v[182:185], 0
	v_mfma_f32_16x16x32_bf16 v[66:69], v[130:133], v[190:193], 0
	v_mfma_f32_16x16x32_bf16 v[8:11], v[138:141], v[190:193], 0
	v_mfma_f32_16x16x32_bf16 v[90:93], v[130:133], v[198:201], 0
	v_mfma_f32_16x16x32_bf16 v[26:29], v[138:141], v[198:201], 0
	v_mfma_f32_16x16x32_bf16 v[86:89], v[134:137], v[166:169], v[86:89]
	v_mfma_f32_16x16x32_bf16 v[22:25], v[142:145], v[166:169], v[22:25]
	v_mfma_f32_16x16x32_bf16 v[70:73], v[134:137], v[186:189], v[70:73]
	v_mfma_f32_16x16x32_bf16 v[12:15], v[142:145], v[186:189], v[12:15]
	v_mfma_f32_16x16x32_bf16 v[66:69], v[134:137], v[194:197], v[66:69]
	v_mfma_f32_16x16x32_bf16 v[8:11], v[142:145], v[194:197], v[8:11]
	v_mfma_f32_16x16x32_bf16 v[90:93], v[134:137], v[202:205], v[90:93]
	v_mfma_f32_16x16x32_bf16 v[26:29], v[142:145], v[202:205], v[26:29]
	v_mfma_f32_16x16x32_bf16 v[74:77], v[146:149], v[162:165], 0
	v_mfma_f32_16x16x32_bf16 v[16:19], v[154:157], v[162:165], 0
	v_mfma_f32_16x16x32_bf16 v[62:65], v[146:149], v[182:185], 0
	v_mfma_f32_16x16x32_bf16 v[4:7], v[154:157], v[182:185], 0
	v_mfma_f32_16x16x32_bf16 v[58:61], v[146:149], v[190:193], 0
	v_mfma_f32_16x16x32_bf16 v[0:3], v[154:157], v[190:193], 0
	v_mfma_f32_16x16x32_bf16 v[94:97], v[146:149], v[198:201], 0
	v_mfma_f32_16x16x32_bf16 v[30:33], v[154:157], v[198:201], 0
	v_mfma_f32_16x16x32_bf16 v[74:77], v[150:153], v[166:169], v[74:77]
	v_mfma_f32_16x16x32_bf16 v[16:19], v[158:161], v[166:169], v[16:19]
	v_mfma_f32_16x16x32_bf16 v[62:65], v[150:153], v[186:189], v[62:65]
	v_mfma_f32_16x16x32_bf16 v[4:7], v[158:161], v[186:189], v[4:7]
	v_mfma_f32_16x16x32_bf16 v[58:61], v[150:153], v[194:197], v[58:61]
	v_mfma_f32_16x16x32_bf16 v[0:3], v[158:161], v[194:197], v[0:3]
	v_mfma_f32_16x16x32_bf16 v[94:97], v[150:153], v[202:205], v[94:97]
	v_mfma_f32_16x16x32_bf16 v[30:33], v[158:161], v[202:205], v[30:33]
	s_barrier
	s_setprio 0
	s_add_i32 vcc_hi, 0, 0x18000
	s_add_i32 s30, 0, 0x1c000
	v_add_u32_e32 v142, vcc_hi, v21
	v_add_u32_e32 v158, s30, v21
	ds_read_b128 v[130:133], v142
	ds_read_b128 v[134:137], v142 offset:1024
	ds_read_b128 v[138:141], v142 offset:2048
	ds_read_b128 v[142:145], v142 offset:3072
	ds_read_b128 v[146:149], v158
	ds_read_b128 v[150:153], v158 offset:1024
	ds_read_b128 v[154:157], v158 offset:2048
	ds_read_b128 v[158:161], v158 offset:3072
	s_add_u32 s24, s78, 0x80000
	s_addc_u32 s25, s79, 0
	s_mov_b32 m0, s38
	v_lshl_add_u64 v[218:219], s[24:25], 0, v[170:171]
	ds_read_b128 v[162:165], v254 offset:32768
	ds_read_b128 v[166:169], v254 offset:33792
	ds_read_b128 v[182:185], v254 offset:34816
	ds_read_b128 v[186:189], v254 offset:35840
	ds_read_b128 v[190:193], v254 offset:36864
	ds_read_b128 v[194:197], v254 offset:37888
	ds_read_b128 v[198:201], v254 offset:38912
	ds_read_b128 v[202:205], v254 offset:39936
	global_load_lds_dwordx4 v[218:219], off
	v_lshl_add_u64 v[218:219], s[24:25], 0, v[174:175]
	s_mov_b32 m0, s39
	s_nop 0
	global_load_lds_dwordx4 v[218:219], off
	s_waitcnt vmcnt(8)
	s_waitcnt lgkmcnt(0)
	s_setprio 1
	s_barrier
	v_mfma_f32_16x16x32_bf16 v[126:129], v[130:133], v[162:165], v[126:129]
	v_mfma_f32_16x16x32_bf16 v[82:85], v[138:141], v[162:165], v[82:85]
	v_mfma_f32_16x16x32_bf16 v[110:113], v[130:133], v[182:185], v[110:113]
	v_mfma_f32_16x16x32_bf16 v[46:49], v[138:141], v[182:185], v[46:49]
	v_mfma_f32_16x16x32_bf16 v[106:109], v[130:133], v[190:193], v[106:109]
	v_mfma_f32_16x16x32_bf16 v[42:45], v[138:141], v[190:193], v[42:45]
	v_mfma_f32_16x16x32_bf16 v[114:117], v[130:133], v[198:201], v[114:117]
	v_mfma_f32_16x16x32_bf16 v[50:53], v[138:141], v[198:201], v[50:53]
	v_mfma_f32_16x16x32_bf16 v[126:129], v[134:137], v[166:169], v[126:129]
	v_mfma_f32_16x16x32_bf16 v[82:85], v[142:145], v[166:169], v[82:85]
	v_mfma_f32_16x16x32_bf16 v[110:113], v[134:137], v[186:189], v[110:113]
	v_mfma_f32_16x16x32_bf16 v[46:49], v[142:145], v[186:189], v[46:49]
	v_mfma_f32_16x16x32_bf16 v[106:109], v[134:137], v[194:197], v[106:109]
	v_mfma_f32_16x16x32_bf16 v[42:45], v[142:145], v[194:197], v[42:45]
	v_mfma_f32_16x16x32_bf16 v[114:117], v[134:137], v[202:205], v[114:117]
	v_mfma_f32_16x16x32_bf16 v[50:53], v[142:145], v[202:205], v[50:53]
	v_mfma_f32_16x16x32_bf16 v[122:125], v[146:149], v[162:165], v[122:125]
	v_mfma_f32_16x16x32_bf16 v[78:81], v[154:157], v[162:165], v[78:81]
	v_mfma_f32_16x16x32_bf16 v[102:105], v[146:149], v[182:185], v[102:105]
	v_mfma_f32_16x16x32_bf16 v[38:41], v[154:157], v[182:185], v[38:41]
	v_mfma_f32_16x16x32_bf16 v[98:101], v[146:149], v[190:193], v[98:101]
	v_mfma_f32_16x16x32_bf16 v[34:37], v[154:157], v[190:193], v[34:37]
	v_mfma_f32_16x16x32_bf16 v[118:121], v[146:149], v[198:201], v[118:121]
	v_mfma_f32_16x16x32_bf16 v[54:57], v[154:157], v[198:201], v[54:57]
	v_mfma_f32_16x16x32_bf16 v[122:125], v[150:153], v[166:169], v[122:125]
	v_mfma_f32_16x16x32_bf16 v[78:81], v[158:161], v[166:169], v[78:81]
	v_mfma_f32_16x16x32_bf16 v[102:105], v[150:153], v[186:189], v[102:105]
	v_mfma_f32_16x16x32_bf16 v[38:41], v[158:161], v[186:189], v[38:41]
	v_mfma_f32_16x16x32_bf16 v[98:101], v[150:153], v[194:197], v[98:101]
	v_mfma_f32_16x16x32_bf16 v[34:37], v[158:161], v[194:197], v[34:37]
	v_mfma_f32_16x16x32_bf16 v[118:121], v[150:153], v[202:205], v[118:121]
	v_mfma_f32_16x16x32_bf16 v[54:57], v[158:161], v[202:205], v[54:57]
	s_barrier
; #define PG8_STAGE(bufoff, gbase, voff) do { _Pragma("unroll") for (int _i = 0; _i < 2; ++_i) \
;         __builtin_amdgcn_global_load_lds((const unsigned*)((const char*)(gbase) + (voff)[_i]), (PG8_LAS unsigned*)(lds + (bufoff) + ldsw + _i * 8192), 16, 0, 0); } while (0)
; #define PG8_LDA(dst, b, h) do { _Pragma("unroll") for (int m = 0; m < 4; ++m) _Pragma("unroll") for (int k = 0; k < 2; ++k) dst[m][k] = *(const PG8_LAS bf16x8*)(lds + PG8_SA(b, h) + aoff + m * 2048 + k * 1024); } while (0)
; #define PG8_MMA(ai, bj, At, Bt) do { __builtin_amdgcn_s_setprio(1); _Pragma("unroll") for (int m = 0; m < 4; ++m) _Pragma("unroll") for (int n = 0; n < 2; ++n) _Pragma("unroll") for (int k = 0; k < 2; ++k) \
;         acc[ai][bj][m][n] = __builtin_amdgcn_mfma_f32_16x16x32_bf16(Bt[n][k], At[m][k], acc[ai][bj][m][n], 0, 0, 0); __builtin_amdgcn_s_setprio(0); } while (0)
; #define PG8_WAIT_V(n) asm volatile("s_waitcnt vmcnt(" #n ")" ::: "memory")
; #define PG8_WAIT_L(n) asm volatile("s_waitcnt lgkmcnt(" #n ")" ::: "memory")
; #define PG8_BAR __builtin_amdgcn_s_barrier()
; #define PG8_SCHED __builtin_amdgcn_sched_barrier(0)
; template <class Epi, class Sched, bool ALIGN_EPI = false, bool SP2 = false>
; __device__ __forceinline__ void gemm_phase(PG8_LAS unsigned char* lds, const Gemm g, const Sched& S, const Epi& E, int tid_in) {
;     ...
;             PG8_LDA(At, 1, 1); PG8_STAGE(PG8_SB(1, 0), b3, voffB); PG8_STAGE(PG8_SB(1, 1), b3 + hstep, voffB); PG8_STAGE(PG8_SA(1, 0), a3, voffA);
;             PG8_WAIT_V(8); PG8_WAIT_L(0); PG8_BAR; PG8_MMA(1, 0, At, B0); PG8_MMA(1, 1, At, B1); PG8_BAR; PG8_SCHED;
	s_setprio 0
	s_add_i32 s24, vcc_hi, s85
	v_lshl_add_u64 v[206:207], v[206:207], 0, s[22:23]
	s_mov_b32 m0, s24
	ds_read_b128 v[162:165], v254 offset:49152
	ds_read_b128 v[166:169], v254 offset:50176
	ds_read_b128 v[182:185], v254 offset:51200
	ds_read_b128 v[186:189], v254 offset:52224
	ds_read_b128 v[190:193], v254 offset:53248
	ds_read_b128 v[194:197], v254 offset:54272
	ds_read_b128 v[198:201], v254 offset:55296
	ds_read_b128 v[202:205], v254 offset:56320
	global_load_lds_dwordx4 v[206:207], off
	s_add_i32 m0, s24, 0x2000
	s_add_u32 s10, s10, 0x80080
	v_lshl_add_u64 v[206:207], v[208:209], 0, s[22:23]
	s_addc_u32 s11, s11, 0
	s_add_i32 s24, s30, s85
	global_load_lds_dwordx4 v[206:207], off
	v_lshl_add_u64 v[206:207], s[10:11], 0, v[172:173]
	s_mov_b32 m0, s24
	s_nop 0
	global_load_lds_dwordx4 v[206:207], off
	v_lshl_add_u64 v[206:207], s[10:11], 0, v[176:177]
	s_add_i32 m0, s24, 0x2000
	s_nop 0
	global_load_lds_dwordx4 v[206:207], off
	v_lshl_add_u64 v[206:207], v[210:211], 0, s[22:23]
	s_mov_b32 m0, s26
	s_nop 0
	global_load_lds_dwordx4 v[206:207], off
	v_lshl_add_u64 v[206:207], v[212:213], 0, s[22:23]
	s_mov_b32 m0, s90
	s_nop 0
	global_load_lds_dwordx4 v[206:207], off
	s_waitcnt vmcnt(8)
	s_waitcnt lgkmcnt(0)
	s_setprio 1
	s_barrier
	v_mfma_f32_16x16x32_bf16 v[86:89], v[130:133], v[162:165], v[86:89]
	v_mfma_f32_16x16x32_bf16 v[22:25], v[138:141], v[162:165], v[22:25]
	v_mfma_f32_16x16x32_bf16 v[70:73], v[130:133], v[182:185], v[70:73]
	v_mfma_f32_16x16x32_bf16 v[12:15], v[138:141], v[182:185], v[12:15]
	v_mfma_f32_16x16x32_bf16 v[66:69], v[130:133], v[190:193], v[66:69]
	v_mfma_f32_16x16x32_bf16 v[8:11], v[138:141], v[190:193], v[8:11]
	v_mfma_f32_16x16x32_bf16 v[90:93], v[130:133], v[198:201], v[90:93]
	v_mfma_f32_16x16x32_bf16 v[26:29], v[138:141], v[198:201], v[26:29]
	v_mfma_f32_16x16x32_bf16 v[86:89], v[134:137], v[166:169], v[86:89]
	v_mfma_f32_16x16x32_bf16 v[22:25], v[142:145], v[166:169], v[22:25]
	v_mfma_f32_16x16x32_bf16 v[70:73], v[134:137], v[186:189], v[70:73]
	v_mfma_f32_16x16x32_bf16 v[12:15], v[142:145], v[186:189], v[12:15]
	v_mfma_f32_16x16x32_bf16 v[66:69], v[134:137], v[194:197], v[66:69]
	v_mfma_f32_16x16x32_bf16 v[8:11], v[142:145], v[194:197], v[8:11]
	v_mfma_f32_16x16x32_bf16 v[90:93], v[134:137], v[202:205], v[90:93]
	v_mfma_f32_16x16x32_bf16 v[26:29], v[142:145], v[202:205], v[26:29]
	v_mfma_f32_16x16x32_bf16 v[74:77], v[146:149], v[162:165], v[74:77]
	v_mfma_f32_16x16x32_bf16 v[16:19], v[154:157], v[162:165], v[16:19]
	v_mfma_f32_16x16x32_bf16 v[62:65], v[146:149], v[182:185], v[62:65]
	v_mfma_f32_16x16x32_bf16 v[4:7], v[154:157], v[182:185], v[4:7]
	v_mfma_f32_16x16x32_bf16 v[58:61], v[146:149], v[190:193], v[58:61]
	v_mfma_f32_16x16x32_bf16 v[0:3], v[154:157], v[190:193], v[0:3]
	v_mfma_f32_16x16x32_bf16 v[94:97], v[146:149], v[198:201], v[94:97]
	v_mfma_f32_16x16x32_bf16 v[30:33], v[154:157], v[198:201], v[30:33]
	v_mfma_f32_16x16x32_bf16 v[74:77], v[150:153], v[166:169], v[74:77]
	v_mfma_f32_16x16x32_bf16 v[16:19], v[158:161], v[166:169], v[16:19]
	v_mfma_f32_16x16x32_bf16 v[62:65], v[150:153], v[186:189], v[62:65]
	v_mfma_f32_16x16x32_bf16 v[4:7], v[158:161], v[186:189], v[4:7]
	v_mfma_f32_16x16x32_bf16 v[58:61], v[150:153], v[194:197], v[58:61]
	v_mfma_f32_16x16x32_bf16 v[0:3], v[158:161], v[194:197], v[0:3]
	v_mfma_f32_16x16x32_bf16 v[94:97], v[150:153], v[202:205], v[94:97]
	v_mfma_f32_16x16x32_bf16 v[30:33], v[158:161], v[202:205], v[30:33]
	s_barrier
	s_setprio 0
	s_add_i32 vcc_lo, vcc_lo, 2
	s_add_u32 s6, s6, 0x100
	s_addc_u32 s7, s7, 0
	s_add_u32 s80, s80, 0x100
	s_addc_u32 s81, s81, 0
	s_cmp_gt_u32 vcc_lo, 29

; #define PG8_STAGE(bufoff, gbase, voff) do { _Pragma("unroll") for (int _i = 0; _i < 2; ++_i) \
;         __builtin_amdgcn_global_load_lds((const unsigned*)((const char*)(gbase) + (voff)[_i]), (PG8_LAS unsigned*)(lds + (bufoff) + ldsw + _i * 8192), 16, 0, 0); } while (0)
; #define PG8_LDA(dst, b, h) do { _Pragma("unroll") for (int m = 0; m < 4; ++m) _Pragma("unroll") for (int k = 0; k < 2; ++k) dst[m][k] = *(const PG8_LAS bf16x8*)(lds + PG8_SA(b, h) + aoff + m * 2048 + k * 1024); } while (0)
; #define PG8_LDB(dst, b, h) do { _Pragma("unroll") for (int n = 0; n < 2; ++n) _Pragma("unroll") for (int k = 0; k < 2; ++k) dst[n][k] = *(const PG8_LAS bf16x8*)(lds + PG8_SB(b, h) + boff + n * 2048 + k * 1024); } while (0)
; template <class Epi, class Sched, bool ALIGN_EPI = false, bool SP2 = false>
; __device__ __forceinline__ void gemm_phase(PG8_LAS unsigned char* lds, const Gemm g, const Sched& S, const Epi& E, int tid_in) {
;     ...
;         const bool has_next = S.next(ui + 1, nxt);
;         const char* nA = has_next ? (const char*)g.A + (size_t)nxt.pm * tstep : cA; const char* nB = has_next ? (const char*)g.Bt + (size_t)nxt.pn * tstep : cB;
;         for (int t = 0; t < nt; t += 2) {
;             const bool last = (t == nt - 2);
;             const char* a1 = cA + (size_t)(t + 1) * kstep;
;             const char* a2 = last ? nA : cA + (size_t)(t + 2) * kstep; const char* b2 = last ? nB : cB + (size_t)(t + 2) * kstep;
;             const char* a3 = a2 + kstep; const char* b3 = b2 + kstep;
;             if (last && has_next) S.a_ready(nxt);
;             if constexpr (SP2) {
;             PG8_LDB(B0, 0, 0); PG8_LDB(B1, 0, 1); PG8_SCHED; PG8_LDA(At, 0, 0); PG8_STAGE(PG8_SA(1, 1), a1 + hstep, voffA);
;             PG8_WAIT_V(8); PG8_WAIT_L(0); PG8_BAR; PG8_MMA(0, 0, At, B0); PG8_MMA(0, 1, At, B1); PG8_BAR; PG8_SCHED;
;             PG8_LDA(At, 0, 1); PG8_STAGE(PG8_SB(0, 0), b2, voffB); PG8_STAGE(PG8_SB(0, 1), b2 + hstep, voffB); PG8_STAGE(PG8_SA(0, 0), a2, voffA);
;             PG8_WAIT_V(8); PG8_WAIT_L(0); PG8_BAR; PG8_MMA(1, 0, At, B0); PG8_MMA(1, 1, At, B1); PG8_BAR; PG8_SCHED;
;     ...
; #pragma unroll
;         for (int a = 0; a < 2; ++a)
; #pragma unroll
;             for (int b = 0; b < 2; ++b)
; #pragma unroll
;                 for (int m = 0; m < 4; ++m)
; #pragma unroll
;                     for (int n = 0; n < 2; ++n) acc[a][b][m][n] = (f32x4){0.f, 0.f, 0.f, 0.f};
.LBB0_890:
	s_add_u32 s69, s10, 0x100
	s_addc_u32 s78, s11, 0
	s_mov_b32 s79, -2
	s_waitcnt vmcnt(0)
	s_add_u32 s6, s8, 0x100
	s_addc_u32 s7, s9, 0
	s_add_i32 s24, 0, 0x10000
	s_cmpk_eq_i32 s79, 0x54
	s_cselect_b32 s67, s63, s7
	s_cselect_b32 s66, s62, s6
	s_cselect_b32 s11, s65, s78
	s_cselect_b32 s10, s64, s69
	s_add_i32 s25, 0, 0x14000
	v_add_u32_e32 v102, s24, v21
	v_add_u32_e32 v150, s25, v21
	ds_read_b128 v[66:69], v102
	ds_read_b128 v[78:81], v102 offset:1024
	ds_read_b128 v[90:93], v102 offset:2048
	ds_read_b128 v[102:105], v102 offset:3072
	ds_read_b128 v[114:117], v150
	ds_read_b128 v[126:129], v150 offset:1024
	ds_read_b128 v[138:141], v150 offset:2048
	ds_read_b128 v[150:153], v150 offset:3072
	v_lshl_add_u64 v[206:207], s[8:9], 0, v[198:199]
	s_add_i32 m0, s34, 0xc000
	ds_read_b128 v[162:165], v228
	ds_read_b128 v[166:169], v228 offset:1024
	ds_read_b128 v[170:173], v228 offset:2048
	ds_read_b128 v[174:177], v228 offset:3072
	ds_read_b128 v[178:181], v228 offset:4096
	ds_read_b128 v[182:185], v228 offset:5120
	ds_read_b128 v[186:189], v228 offset:6144
	ds_read_b128 v[202:205], v228 offset:7168
	global_load_lds_dwordx4 v[206:207], off
	v_lshl_add_u64 v[206:207], s[8:9], 0, v[200:201]
	s_add_i32 m0, s34, 0xe000
	s_nop 0
	global_load_lds_dwordx4 v[206:207], off
	s_waitcnt vmcnt(8)
	s_waitcnt lgkmcnt(0)
	s_setprio 1
	s_barrier
	v_mfma_f32_16x16x32_bf16 v[158:161], v[66:69], v[162:165], 0
	v_mfma_f32_16x16x32_bf16 v[154:157], v[90:93], v[162:165], 0
	v_mfma_f32_16x16x32_bf16 v[134:137], v[66:69], v[170:173], 0
	v_mfma_f32_16x16x32_bf16 v[130:133], v[90:93], v[170:173], 0
	v_mfma_f32_16x16x32_bf16 v[110:113], v[66:69], v[178:181], 0
	v_mfma_f32_16x16x32_bf16 v[106:109], v[90:93], v[178:181], 0
	v_mfma_f32_16x16x32_bf16 v[86:89], v[66:69], v[186:189], 0
	v_mfma_f32_16x16x32_bf16 v[82:85], v[90:93], v[186:189], 0
	v_mfma_f32_16x16x32_bf16 v[158:161], v[78:81], v[166:169], v[158:161]
	v_mfma_f32_16x16x32_bf16 v[154:157], v[102:105], v[166:169], v[154:157]
	v_mfma_f32_16x16x32_bf16 v[134:137], v[78:81], v[174:177], v[134:137]
	v_mfma_f32_16x16x32_bf16 v[130:133], v[102:105], v[174:177], v[130:133]
	v_mfma_f32_16x16x32_bf16 v[110:113], v[78:81], v[182:185], v[110:113]
	v_mfma_f32_16x16x32_bf16 v[106:109], v[102:105], v[182:185], v[106:109]
	v_mfma_f32_16x16x32_bf16 v[86:89], v[78:81], v[202:205], v[86:89]
	v_mfma_f32_16x16x32_bf16 v[82:85], v[102:105], v[202:205], v[82:85]
	v_mfma_f32_16x16x32_bf16 v[146:149], v[114:117], v[162:165], 0
	v_mfma_f32_16x16x32_bf16 v[142:145], v[138:141], v[162:165], 0
	v_mfma_f32_16x16x32_bf16 v[122:125], v[114:117], v[170:173], 0
	v_mfma_f32_16x16x32_bf16 v[118:121], v[138:141], v[170:173], 0
	v_mfma_f32_16x16x32_bf16 v[98:101], v[114:117], v[178:181], 0
	v_mfma_f32_16x16x32_bf16 v[94:97], v[138:141], v[178:181], 0
	v_mfma_f32_16x16x32_bf16 v[74:77], v[114:117], v[186:189], 0
	v_mfma_f32_16x16x32_bf16 v[70:73], v[138:141], v[186:189], 0
	v_mfma_f32_16x16x32_bf16 v[146:149], v[126:129], v[166:169], v[146:149]
	v_mfma_f32_16x16x32_bf16 v[142:145], v[150:153], v[166:169], v[142:145]
	v_mfma_f32_16x16x32_bf16 v[122:125], v[126:129], v[174:177], v[122:125]
	v_mfma_f32_16x16x32_bf16 v[118:121], v[150:153], v[174:177], v[118:121]
	v_mfma_f32_16x16x32_bf16 v[98:101], v[126:129], v[182:185], v[98:101]
	v_mfma_f32_16x16x32_bf16 v[94:97], v[150:153], v[182:185], v[94:97]
	v_mfma_f32_16x16x32_bf16 v[74:77], v[126:129], v[202:205], v[74:77]
	v_mfma_f32_16x16x32_bf16 v[70:73], v[150:153], v[202:205], v[70:73]
	s_barrier
	s_setprio 0
	s_add_i32 s8, s24, s14
	v_lshl_add_u64 v[206:207], s[10:11], 0, v[192:193]
	s_mov_b32 m0, s8
	ds_read_b128 v[162:165], v228 offset:16384
	ds_read_b128 v[166:169], v228 offset:17408
	ds_read_b128 v[170:173], v228 offset:18432
	ds_read_b128 v[174:177], v228 offset:19456
	ds_read_b128 v[178:181], v228 offset:20480
	ds_read_b128 v[182:185], v228 offset:21504
	ds_read_b128 v[186:189], v228 offset:22528
	ds_read_b128 v[202:205], v228 offset:23552
	global_load_lds_dwordx4 v[206:207], off
	s_add_i32 m0, s8, 0x2000
	s_add_u32 s8, s10, 0x160000
	v_lshl_add_u64 v[208:209], s[10:11], 0, v[196:197]
	s_addc_u32 s9, s11, 0
	s_add_i32 s24, s25, s14
	global_load_lds_dwordx4 v[208:209], off
	v_lshl_add_u64 v[210:211], s[8:9], 0, v[192:193]
	s_mov_b32 m0, s24
	v_lshl_add_u64 v[212:213], s[66:67], 0, v[194:195]
	global_load_lds_dwordx4 v[210:211], off
	v_lshl_add_u64 v[210:211], s[8:9], 0, v[196:197]
	s_add_i32 m0, s24, 0x2000
	s_nop 0
	global_load_lds_dwordx4 v[210:211], off
	v_lshl_add_u64 v[210:211], s[66:67], 0, v[190:191]
	s_mov_b32 m0, s34
	s_nop 0
	global_load_lds_dwordx4 v[210:211], off
	s_mov_b32 m0, s35
	s_nop 0
	global_load_lds_dwordx4 v[212:213], off
	s_waitcnt vmcnt(8)
	s_waitcnt lgkmcnt(0)
	s_setprio 1
	s_barrier
; #define PG8_STAGE(bufoff, gbase, voff) do { _Pragma("unroll") for (int _i = 0; _i < 2; ++_i) \
;         __builtin_amdgcn_global_load_lds((const unsigned*)((const char*)(gbase) + (voff)[_i]), (PG8_LAS unsigned*)(lds + (bufoff) + ldsw + _i * 8192), 16, 0, 0); } while (0)
; #define PG8_LDA(dst, b, h) do { _Pragma("unroll") for (int m = 0; m < 4; ++m) _Pragma("unroll") for (int k = 0; k < 2; ++k) dst[m][k] = *(const PG8_LAS bf16x8*)(lds + PG8_SA(b, h) + aoff + m * 2048 + k * 1024); } while (0)
; #define PG8_LDB(dst, b, h) do { _Pragma("unroll") for (int n = 0; n < 2; ++n) _Pragma("unroll") for (int k = 0; k < 2; ++k) dst[n][k] = *(const PG8_LAS bf16x8*)(lds + PG8_SB(b, h) + boff + n * 2048 + k * 1024); } while (0)
; #define PG8_MMA(ai, bj, At, Bt) do { __builtin_amdgcn_s_setprio(1); _Pragma("unroll") for (int m = 0; m < 4; ++m) _Pragma("unroll") for (int n = 0; n < 2; ++n) _Pragma("unroll") for (int k = 0; k < 2; ++k) \
;         acc[ai][bj][m][n] = __builtin_amdgcn_mfma_f32_16x16x32_bf16(Bt[n][k], At[m][k], acc[ai][bj][m][n], 0, 0, 0); __builtin_amdgcn_s_setprio(0); } while (0)
; #define PG8_WAIT_V(n) asm volatile("s_waitcnt vmcnt(" #n ")" ::: "memory")
; #define PG8_WAIT_L(n) asm volatile("s_waitcnt lgkmcnt(" #n ")" ::: "memory")
; #define PG8_BAR __builtin_amdgcn_s_barrier()
; #define PG8_SCHED __builtin_amdgcn_sched_barrier(0)
; template <class Epi, class Sched, bool ALIGN_EPI = false, bool SP2 = false>
; __device__ __forceinline__ void gemm_phase(PG8_LAS unsigned char* lds, const Gemm g, const Sched& S, const Epi& E, int tid_in) {
;     ...
;             PG8_WAIT_V(8); PG8_WAIT_L(0); PG8_BAR; PG8_MMA(1, 0, At, B0); PG8_MMA(1, 1, At, B1); PG8_BAR; PG8_SCHED;
;             PG8_LDB(B0, 1, 0); PG8_LDB(B1, 1, 1); PG8_SCHED; PG8_LDA(At, 1, 0); PG8_STAGE(PG8_SA(0, 1), a2 + hstep, voffA);
;             PG8_WAIT_V(8); PG8_WAIT_L(0); PG8_BAR; PG8_MMA(0, 0, At, B0); PG8_MMA(0, 1, At, B1); PG8_BAR; PG8_SCHED;
	v_mfma_f32_16x16x32_bf16 v[62:65], v[66:69], v[162:165], 0
	v_mfma_f32_16x16x32_bf16 v[58:61], v[90:93], v[162:165], 0
	v_mfma_f32_16x16x32_bf16 v[46:49], v[66:69], v[170:173], 0
	v_mfma_f32_16x16x32_bf16 v[42:45], v[90:93], v[170:173], 0
	v_mfma_f32_16x16x32_bf16 v[30:33], v[66:69], v[178:181], 0
	v_mfma_f32_16x16x32_bf16 v[26:29], v[90:93], v[178:181], 0
	v_mfma_f32_16x16x32_bf16 v[12:15], v[66:69], v[186:189], 0
	v_mfma_f32_16x16x32_bf16 v[8:11], v[90:93], v[186:189], 0
	v_mfma_f32_16x16x32_bf16 v[62:65], v[78:81], v[166:169], v[62:65]
	v_mfma_f32_16x16x32_bf16 v[58:61], v[102:105], v[166:169], v[58:61]
	v_mfma_f32_16x16x32_bf16 v[46:49], v[78:81], v[174:177], v[46:49]
	v_mfma_f32_16x16x32_bf16 v[42:45], v[102:105], v[174:177], v[42:45]
	v_mfma_f32_16x16x32_bf16 v[30:33], v[78:81], v[182:185], v[30:33]
	v_mfma_f32_16x16x32_bf16 v[26:29], v[102:105], v[182:185], v[26:29]
	v_mfma_f32_16x16x32_bf16 v[12:15], v[78:81], v[202:205], v[12:15]
	v_mfma_f32_16x16x32_bf16 v[8:11], v[102:105], v[202:205], v[8:11]
	v_mfma_f32_16x16x32_bf16 v[54:57], v[114:117], v[162:165], 0
	v_mfma_f32_16x16x32_bf16 v[50:53], v[138:141], v[162:165], 0
	v_mfma_f32_16x16x32_bf16 v[38:41], v[114:117], v[170:173], 0
	v_mfma_f32_16x16x32_bf16 v[34:37], v[138:141], v[170:173], 0
	v_mfma_f32_16x16x32_bf16 v[22:25], v[114:117], v[178:181], 0
	v_mfma_f32_16x16x32_bf16 v[16:19], v[138:141], v[178:181], 0
	v_mfma_f32_16x16x32_bf16 v[4:7], v[114:117], v[186:189], 0
	v_mfma_f32_16x16x32_bf16 v[0:3], v[138:141], v[186:189], 0
	v_mfma_f32_16x16x32_bf16 v[54:57], v[126:129], v[166:169], v[54:57]
	v_mfma_f32_16x16x32_bf16 v[50:53], v[150:153], v[166:169], v[50:53]
	v_mfma_f32_16x16x32_bf16 v[38:41], v[126:129], v[174:177], v[38:41]
	v_mfma_f32_16x16x32_bf16 v[34:37], v[150:153], v[174:177], v[34:37]
	v_mfma_f32_16x16x32_bf16 v[22:25], v[126:129], v[182:185], v[22:25]
	v_mfma_f32_16x16x32_bf16 v[16:19], v[150:153], v[182:185], v[16:19]
	v_mfma_f32_16x16x32_bf16 v[4:7], v[126:129], v[202:205], v[4:7]
	v_mfma_f32_16x16x32_bf16 v[0:3], v[150:153], v[202:205], v[0:3]
	s_barrier
	s_setprio 0
	s_add_i32 s24, 0, 0x18000
	s_add_i32 s25, 0, 0x1c000
	v_add_u32_e32 v102, s24, v21
	v_add_u32_e32 v150, s25, v21
	ds_read_b128 v[66:69], v102
	ds_read_b128 v[78:81], v102 offset:1024
	ds_read_b128 v[90:93], v102 offset:2048
	ds_read_b128 v[102:105], v102 offset:3072
	ds_read_b128 v[114:117], v150
	ds_read_b128 v[126:129], v150 offset:1024
	ds_read_b128 v[138:141], v150 offset:2048
	ds_read_b128 v[150:153], v150 offset:3072
	s_add_u32 s8, s66, 0x160000
	s_addc_u32 s9, s67, 0
	s_mov_b32 m0, s37
	v_lshl_add_u64 v[218:219], s[8:9], 0, v[190:191]
	ds_read_b128 v[162:165], v228 offset:32768
	ds_read_b128 v[166:169], v228 offset:33792
	ds_read_b128 v[170:173], v228 offset:34816
	ds_read_b128 v[174:177], v228 offset:35840
	ds_read_b128 v[178:181], v228 offset:36864
	ds_read_b128 v[182:185], v228 offset:37888
	ds_read_b128 v[186:189], v228 offset:38912
	ds_read_b128 v[202:205], v228 offset:39936
	global_load_lds_dwordx4 v[218:219], off
	v_lshl_add_u64 v[218:219], s[8:9], 0, v[194:195]
	s_mov_b32 m0, s38
	s_nop 0
	global_load_lds_dwordx4 v[218:219], off
	s_waitcnt vmcnt(8)
	s_waitcnt lgkmcnt(0)
	s_setprio 1
	s_barrier
	v_mfma_f32_16x16x32_bf16 v[158:161], v[66:69], v[162:165], v[158:161]
	v_mfma_f32_16x16x32_bf16 v[154:157], v[90:93], v[162:165], v[154:157]
	v_mfma_f32_16x16x32_bf16 v[134:137], v[66:69], v[170:173], v[134:137]
	v_mfma_f32_16x16x32_bf16 v[130:133], v[90:93], v[170:173], v[130:133]
	v_mfma_f32_16x16x32_bf16 v[110:113], v[66:69], v[178:181], v[110:113]
	v_mfma_f32_16x16x32_bf16 v[106:109], v[90:93], v[178:181], v[106:109]
	v_mfma_f32_16x16x32_bf16 v[86:89], v[66:69], v[186:189], v[86:89]
	v_mfma_f32_16x16x32_bf16 v[82:85], v[90:93], v[186:189], v[82:85]
	v_mfma_f32_16x16x32_bf16 v[158:161], v[78:81], v[166:169], v[158:161]
	v_mfma_f32_16x16x32_bf16 v[154:157], v[102:105], v[166:169], v[154:157]
	v_mfma_f32_16x16x32_bf16 v[134:137], v[78:81], v[174:177], v[134:137]
	v_mfma_f32_16x16x32_bf16 v[130:133], v[102:105], v[174:177], v[130:133]
	v_mfma_f32_16x16x32_bf16 v[110:113], v[78:81], v[182:185], v[110:113]
	v_mfma_f32_16x16x32_bf16 v[106:109], v[102:105], v[182:185], v[106:109]
	v_mfma_f32_16x16x32_bf16 v[86:89], v[78:81], v[202:205], v[86:89]
	v_mfma_f32_16x16x32_bf16 v[82:85], v[102:105], v[202:205], v[82:85]
	v_mfma_f32_16x16x32_bf16 v[146:149], v[114:117], v[162:165], v[146:149]
	v_mfma_f32_16x16x32_bf16 v[142:145], v[138:141], v[162:165], v[142:145]
	v_mfma_f32_16x16x32_bf16 v[122:125], v[114:117], v[170:173], v[122:125]
	v_mfma_f32_16x16x32_bf16 v[118:121], v[138:141], v[170:173], v[118:121]
	v_mfma_f32_16x16x32_bf16 v[98:101], v[114:117], v[178:181], v[98:101]
	v_mfma_f32_16x16x32_bf16 v[94:97], v[138:141], v[178:181], v[94:97]
	v_mfma_f32_16x16x32_bf16 v[74:77], v[114:117], v[186:189], v[74:77]
	v_mfma_f32_16x16x32_bf16 v[70:73], v[138:141], v[186:189], v[70:73]
	v_mfma_f32_16x16x32_bf16 v[146:149], v[126:129], v[166:169], v[146:149]
	v_mfma_f32_16x16x32_bf16 v[142:145], v[150:153], v[166:169], v[142:145]
	v_mfma_f32_16x16x32_bf16 v[122:125], v[126:129], v[174:177], v[122:125]
	v_mfma_f32_16x16x32_bf16 v[118:121], v[150:153], v[174:177], v[118:121]
	v_mfma_f32_16x16x32_bf16 v[98:101], v[126:129], v[182:185], v[98:101]
	v_mfma_f32_16x16x32_bf16 v[94:97], v[150:153], v[182:185], v[94:97]
	v_mfma_f32_16x16x32_bf16 v[74:77], v[126:129], v[202:205], v[74:77]
	v_mfma_f32_16x16x32_bf16 v[70:73], v[150:153], v[202:205], v[70:73]
	s_barrier
; #define PG8_STAGE(bufoff, gbase, voff) do { _Pragma("unroll") for (int _i = 0; _i < 2; ++_i) \
;         __builtin_amdgcn_global_load_lds((const unsigned*)((const char*)(gbase) + (voff)[_i]), (PG8_LAS unsigned*)(lds + (bufoff) + ldsw + _i * 8192), 16, 0, 0); } while (0)
; #define PG8_LDA(dst, b, h) do { _Pragma("unroll") for (int m = 0; m < 4; ++m) _Pragma("unroll") for (int k = 0; k < 2; ++k) dst[m][k] = *(const PG8_LAS bf16x8*)(lds + PG8_SA(b, h) + aoff + m * 2048 + k * 1024); } while (0)
; #define PG8_MMA(ai, bj, At, Bt) do { __builtin_amdgcn_s_setprio(1); _Pragma("unroll") for (int m = 0; m < 4; ++m) _Pragma("unroll") for (int n = 0; n < 2; ++n) _Pragma("unroll") for (int k = 0; k < 2; ++k) \
;         acc[ai][bj][m][n] = __builtin_amdgcn_mfma_f32_16x16x32_bf16(Bt[n][k], At[m][k], acc[ai][bj][m][n], 0, 0, 0); __builtin_amdgcn_s_setprio(0); } while (0)
; #define PG8_WAIT_V(n) asm volatile("s_waitcnt vmcnt(" #n ")" ::: "memory")
; #define PG8_WAIT_L(n) asm volatile("s_waitcnt lgkmcnt(" #n ")" ::: "memory")
; #define PG8_BAR __builtin_amdgcn_s_barrier()
; #define PG8_SCHED __builtin_amdgcn_sched_barrier(0)
; template <class Epi, class Sched, bool ALIGN_EPI = false, bool SP2 = false>
; __device__ __forceinline__ void gemm_phase(PG8_LAS unsigned char* lds, const Gemm g, const Sched& S, const Epi& E, int tid_in) {
;     ...
;             PG8_LDA(At, 1, 1); PG8_STAGE(PG8_SB(1, 0), b3, voffB); PG8_STAGE(PG8_SB(1, 1), b3 + hstep, voffB); PG8_STAGE(PG8_SA(1, 0), a3, voffA);
;             PG8_WAIT_V(8); PG8_WAIT_L(0); PG8_BAR; PG8_MMA(1, 0, At, B0); PG8_MMA(1, 1, At, B1); PG8_BAR; PG8_SCHED;
	s_setprio 0
	s_add_i32 s8, s24, s14
	v_lshl_add_u64 v[206:207], v[206:207], 0, s[22:23]
	s_mov_b32 m0, s8
	ds_read_b128 v[162:165], v228 offset:49152
	ds_read_b128 v[166:169], v228 offset:50176
	ds_read_b128 v[170:173], v228 offset:51200
	ds_read_b128 v[174:177], v228 offset:52224
	ds_read_b128 v[178:181], v228 offset:53248
	ds_read_b128 v[182:185], v228 offset:54272
	ds_read_b128 v[186:189], v228 offset:55296
	ds_read_b128 v[202:205], v228 offset:56320
	global_load_lds_dwordx4 v[206:207], off
	s_add_i32 m0, s8, 0x2000
	s_add_u32 s8, s10, 0x160080
	v_lshl_add_u64 v[206:207], v[208:209], 0, s[22:23]
	s_addc_u32 s9, s11, 0
	s_add_i32 s10, s25, s14
	global_load_lds_dwordx4 v[206:207], off
	v_lshl_add_u64 v[206:207], s[8:9], 0, v[192:193]
	s_mov_b32 m0, s10
	s_nop 0
	global_load_lds_dwordx4 v[206:207], off
	v_lshl_add_u64 v[206:207], s[8:9], 0, v[196:197]
	s_add_i32 m0, s10, 0x2000
	s_nop 0
	global_load_lds_dwordx4 v[206:207], off
	v_lshl_add_u64 v[206:207], v[210:211], 0, s[22:23]
	s_mov_b32 m0, s71
	s_nop 0
	global_load_lds_dwordx4 v[206:207], off
	v_lshl_add_u64 v[206:207], v[212:213], 0, s[22:23]
	s_mov_b32 m0, s72
	s_nop 0
	global_load_lds_dwordx4 v[206:207], off
	s_waitcnt vmcnt(8)
	s_waitcnt lgkmcnt(0)
	s_setprio 1
	s_barrier
	v_mfma_f32_16x16x32_bf16 v[62:65], v[66:69], v[162:165], v[62:65]
	v_mfma_f32_16x16x32_bf16 v[58:61], v[90:93], v[162:165], v[58:61]
	v_mfma_f32_16x16x32_bf16 v[46:49], v[66:69], v[170:173], v[46:49]
	v_mfma_f32_16x16x32_bf16 v[42:45], v[90:93], v[170:173], v[42:45]
	v_mfma_f32_16x16x32_bf16 v[30:33], v[66:69], v[178:181], v[30:33]
	v_mfma_f32_16x16x32_bf16 v[26:29], v[90:93], v[178:181], v[26:29]
	v_mfma_f32_16x16x32_bf16 v[12:15], v[66:69], v[186:189], v[12:15]
	v_mfma_f32_16x16x32_bf16 v[8:11], v[90:93], v[186:189], v[8:11]
	v_mfma_f32_16x16x32_bf16 v[62:65], v[78:81], v[166:169], v[62:65]
	v_mfma_f32_16x16x32_bf16 v[58:61], v[102:105], v[166:169], v[58:61]
	v_mfma_f32_16x16x32_bf16 v[46:49], v[78:81], v[174:177], v[46:49]
	v_mfma_f32_16x16x32_bf16 v[42:45], v[102:105], v[174:177], v[42:45]
	v_mfma_f32_16x16x32_bf16 v[30:33], v[78:81], v[182:185], v[30:33]
	v_mfma_f32_16x16x32_bf16 v[26:29], v[102:105], v[182:185], v[26:29]
	v_mfma_f32_16x16x32_bf16 v[12:15], v[78:81], v[202:205], v[12:15]
	v_mfma_f32_16x16x32_bf16 v[8:11], v[102:105], v[202:205], v[8:11]
	v_mfma_f32_16x16x32_bf16 v[54:57], v[114:117], v[162:165], v[54:57]
	v_mfma_f32_16x16x32_bf16 v[50:53], v[138:141], v[162:165], v[50:53]
	v_mfma_f32_16x16x32_bf16 v[38:41], v[114:117], v[170:173], v[38:41]
	v_mfma_f32_16x16x32_bf16 v[34:37], v[138:141], v[170:173], v[34:37]
	v_mfma_f32_16x16x32_bf16 v[22:25], v[114:117], v[178:181], v[22:25]
	v_mfma_f32_16x16x32_bf16 v[16:19], v[138:141], v[178:181], v[16:19]
	v_mfma_f32_16x16x32_bf16 v[4:7], v[114:117], v[186:189], v[4:7]
	v_mfma_f32_16x16x32_bf16 v[0:3], v[138:141], v[186:189], v[0:3]
	v_mfma_f32_16x16x32_bf16 v[54:57], v[126:129], v[166:169], v[54:57]
	v_mfma_f32_16x16x32_bf16 v[50:53], v[150:153], v[166:169], v[50:53]
	v_mfma_f32_16x16x32_bf16 v[38:41], v[126:129], v[174:177], v[38:41]
	v_mfma_f32_16x16x32_bf16 v[34:37], v[150:153], v[174:177], v[34:37]
	v_mfma_f32_16x16x32_bf16 v[22:25], v[126:129], v[182:185], v[22:25]
	v_mfma_f32_16x16x32_bf16 v[16:19], v[150:153], v[182:185], v[16:19]
	v_mfma_f32_16x16x32_bf16 v[4:7], v[126:129], v[202:205], v[4:7]
	v_mfma_f32_16x16x32_bf16 v[0:3], v[150:153], v[202:205], v[0:3]
	s_barrier
	s_setprio 0
	s_add_i32 s79, s79, 2
	s_add_u32 s69, s69, 0x100
	s_addc_u32 s78, s78, 0
	s_cmpk_gt_u32 s79, 0x55
	s_mov_b64 s[8:9], s[6:7]
